# GEMM: first two super-phases after a unit epilogue wait vmcnt(8+stores) instead of vmcnt(8) so the K-loop does not stall on the epilogue store acks (plus redundant zeroing removed)
# speedup vs baseline: 1.0031x; 1.0031x over previous
.LBB0_32:
	s_add_i32 m0, s38, 0x18000
	v_lshl_add_u64 v[0:1], v[0:1], 0, s[98:99]
	s_waitcnt vmcnt(2)
	s_barrier
	global_load_lds_dwordx4 v[0:1], off
	v_lshl_add_u64 v[0:1], v[2:3], 0, s[98:99]
	s_add_i32 m0, s38, 0x1a000
	s_add_i32 s46, s38, 0x8000
	global_load_lds_dwordx4 v[0:1], off
	v_lshl_add_u64 v[0:1], v[8:9], 0, s[98:99]
	s_mov_b32 m0, s46
	s_add_i32 s47, s38, 0xa000
	global_load_lds_dwordx4 v[0:1], off
	v_lshl_add_u64 v[0:1], v[10:11], 0, s[98:99]
	s_mov_b32 m0, s47
	s_lshr_b32 s1, s1, 26
	global_load_lds_dwordx4 v[0:1], off
	s_add_i32 m0, s38, 0x1c000
	v_lshl_add_u64 v[0:1], v[4:5], 0, s[98:99]
	global_load_lds_dwordx4 v[0:1], off
	v_lshl_add_u64 v[0:1], v[6:7], 0, s[98:99]
	s_add_i32 m0, s38, 0x1e000
	s_add_i32 s1, s0, s1
	global_load_lds_dwordx4 v[0:1], off
	v_lshrrev_b32_e32 v1, 1, v12
	v_and_b32_e32 v1, 24, v1
	v_and_b32_e32 v0, 15, v12
	v_lshlrev_b32_e32 v2, 1, v1
	v_lshl_or_b32 v135, s15, 6, v0
	v_lshl_or_b32 v0, v0, 6, v2
	v_lshlrev_b32_e32 v2, 2, v12
	s_ashr_i32 s48, s1, 6
	s_lshl_b32 s1, s15, 13
	v_and_b32_e32 v2, 32, v2
	v_bitop3_b32 v3, v0, s1, v2 bitop3:0xde
	s_lshl_b32 s1, s14, 5
	s_and_b32 s1, s1, 0x60
	s_lshl_b32 s14, s1, 7
	v_bitop3_b32 v137, v0, s14, v2 bitop3:0xde
	v_add_u32_e32 v0, v18, v16
	s_cmp_gt_i32 s0, 63
	v_or_b32_e32 v156, s1, v1
	v_add_lshl_u32 v0, v0, v17, 1
	v_mov_b32_e32 v1, v129
	s_waitcnt vmcnt(6)
	s_cselect_b64 s[14:15], -1, 0
	s_add_i32 s49, s48, -2
	v_lshl_add_u64 v[146:147], s[2:3], 0, v[0:1]
	v_add_u32_e32 v0, v15, v13
	s_cmpk_lt_u32 s16, 0x100
	v_add_lshl_u32 v0, v0, v14, 1
	s_cselect_b64 s[16:17], -1, 0
	s_waitcnt lgkmcnt(0)
	s_ashr_i32 s50, s34, 31
	v_lshl_add_u64 v[148:149], s[2:3], 0, v[0:1]
	s_mov_b32 s51, 0
	v_add_u32_e32 v157, 16, v3
	v_readlane_b32 s54, v254, 48
	v_readlane_b32 s55, v254, 54
	s_barrier
	s_mov_b32 s101, 0
	s_branch .LBB0_35

.LBB0_47:
	s_cmp_eq_u32 s26, 0
	s_cselect_b32 s100, s101, 0
	s_add_i32 s56, s26, 2
	s_add_u32 s57, s0, 0x80
	s_addc_u32 s27, s1, 0
	s_add_i32 s60, 16, 0x10000
	s_cmp_eq_u32 s49, s26
	s_cselect_b32 s27, s21, s27
	s_cselect_b32 s26, s20, s57
	v_add_u32_e32 v154, s60, v137
	s_cselect_b32 s59, s25, s29
	s_cselect_b32 s58, s24, s28
	s_add_i32 s57, 16, 0x14000
	ds_read_b128 v[150:153], v154
	ds_read_b128 v[158:161], v154 offset:1024
	ds_read_b128 v[162:165], v154 offset:2048
	ds_read_b128 v[166:169], v154 offset:3072
	v_add_u32_e32 v154, s57, v137
	ds_read_b128 v[170:173], v154
	ds_read_b128 v[174:177], v154 offset:1024
	ds_read_b128 v[178:181], v154 offset:2048
	ds_read_b128 v[182:185], v154 offset:3072
	v_lshl_add_u64 v[154:155], s[0:1], 0, v[146:147]
	s_add_i32 m0, s38, 0xc000
	ds_read_b128 v[186:189], v157
	ds_read_b128 v[190:193], v157 offset:1024
	ds_read_b128 v[194:197], v157 offset:2048
	ds_read_b128 v[220:223], v157 offset:3072
	ds_read_b128 v[224:227], v157 offset:4096
	ds_read_b128 v[228:231], v157 offset:5120
	ds_read_b128 v[232:235], v157 offset:6144
	ds_read_b128 v[236:239], v157 offset:7168
	global_load_lds_dwordx4 v[154:155], off
	v_lshl_add_u64 v[154:155], s[0:1], 0, v[148:149]
	s_add_i32 m0, s38, 0xe000
	s_nop 0
	global_load_lds_dwordx4 v[154:155], off
	s_cmp_eq_u32 s100, 0
	s_cbranch_scc1 .Lgw8_0_0
	s_cmp_eq_u32 s100, 8
	s_cbranch_scc1 .Lgw16_0_0
	s_waitcnt vmcnt(24)
	s_branch .Lgwd_0_0
.Lgw16_0_0:
	s_waitcnt vmcnt(16)
	s_branch .Lgwd_0_0
.Lgw8_0_0:
	s_waitcnt vmcnt(8)
.Lgwd_0_0:
	s_waitcnt lgkmcnt(0)
	s_barrier
	s_setprio 1
	s_waitcnt lgkmcnt(0)
	v_mfma_f32_16x16x32_bf16 v[120:123], v[150:153], v[186:189], v[120:123]
	v_mfma_f32_16x16x32_bf16 v[124:127], v[162:165], v[186:189], v[124:127]
	v_mfma_f32_16x16x32_bf16 v[108:111], v[150:153], v[194:197], v[108:111]
	v_mfma_f32_16x16x32_bf16 v[104:107], v[162:165], v[194:197], v[104:107]
	v_mfma_f32_16x16x32_bf16 v[92:95], v[150:153], v[224:227], v[92:95]
	v_mfma_f32_16x16x32_bf16 v[88:91], v[162:165], v[224:227], v[88:91]
	v_mfma_f32_16x16x32_bf16 v[76:79], v[150:153], v[232:235], v[76:79]
	v_mfma_f32_16x16x32_bf16 v[72:75], v[162:165], v[232:235], v[72:75]
	v_mfma_f32_16x16x32_bf16 v[120:123], v[158:161], v[190:193], v[120:123]
	v_mfma_f32_16x16x32_bf16 v[124:127], v[166:169], v[190:193], v[124:127]
	v_mfma_f32_16x16x32_bf16 v[108:111], v[158:161], v[220:223], v[108:111]
	v_mfma_f32_16x16x32_bf16 v[104:107], v[166:169], v[220:223], v[104:107]
	v_mfma_f32_16x16x32_bf16 v[92:95], v[158:161], v[228:231], v[92:95]
	v_mfma_f32_16x16x32_bf16 v[88:91], v[166:169], v[228:231], v[88:91]
	v_mfma_f32_16x16x32_bf16 v[76:79], v[158:161], v[236:239], v[76:79]
	v_mfma_f32_16x16x32_bf16 v[72:75], v[166:169], v[236:239], v[72:75]
	s_setprio 0
	s_setprio 1
	v_mfma_f32_16x16x32_bf16 v[116:119], v[170:173], v[186:189], v[116:119]
	v_mfma_f32_16x16x32_bf16 v[112:115], v[178:181], v[186:189], v[112:115]
	v_mfma_f32_16x16x32_bf16 v[100:103], v[170:173], v[194:197], v[100:103]
	v_mfma_f32_16x16x32_bf16 v[96:99], v[178:181], v[194:197], v[96:99]
	v_mfma_f32_16x16x32_bf16 v[84:87], v[170:173], v[224:227], v[84:87]
	v_mfma_f32_16x16x32_bf16 v[80:83], v[178:181], v[224:227], v[80:83]
	v_mfma_f32_16x16x32_bf16 v[68:71], v[170:173], v[232:235], v[68:71]
	v_mfma_f32_16x16x32_bf16 v[64:67], v[178:181], v[232:235], v[64:67]
	v_mfma_f32_16x16x32_bf16 v[116:119], v[174:177], v[190:193], v[116:119]
	v_mfma_f32_16x16x32_bf16 v[112:115], v[182:185], v[190:193], v[112:115]
	v_mfma_f32_16x16x32_bf16 v[100:103], v[174:177], v[220:223], v[100:103]
	v_mfma_f32_16x16x32_bf16 v[96:99], v[182:185], v[220:223], v[96:99]
	v_mfma_f32_16x16x32_bf16 v[84:87], v[174:177], v[228:231], v[84:87]
	v_mfma_f32_16x16x32_bf16 v[80:83], v[182:185], v[228:231], v[80:83]
	v_mfma_f32_16x16x32_bf16 v[68:71], v[174:177], v[236:239], v[68:71]
	v_mfma_f32_16x16x32_bf16 v[64:67], v[182:185], v[236:239], v[64:67]
	s_setprio 0
	s_barrier
	s_add_i32 s60, s60, s35
	v_lshl_add_u64 v[154:155], s[58:59], 0, v[128:129]
	s_mov_b32 m0, s60
	ds_read_b128 v[186:189], v157 offset:16384
	ds_read_b128 v[190:193], v157 offset:17408
	ds_read_b128 v[194:197], v157 offset:18432
	ds_read_b128 v[220:223], v157 offset:19456
	ds_read_b128 v[224:227], v157 offset:20480
	ds_read_b128 v[228:231], v157 offset:21504
	ds_read_b128 v[232:235], v157 offset:22528
	ds_read_b128 v[236:239], v157 offset:23552
	global_load_lds_dwordx4 v[154:155], off
	s_add_i32 m0, s60, 0x2000
	v_lshl_add_u64 v[198:199], s[58:59], 0, v[140:141]
	s_add_u32 s58, s58, s2
	s_addc_u32 s59, s59, s3
	s_add_i32 s57, s57, s35
	global_load_lds_dwordx4 v[198:199], off
	v_lshl_add_u64 v[208:209], s[58:59], 0, v[128:129]
	s_mov_b32 m0, s57
	v_lshl_add_u64 v[244:245], s[58:59], 0, v[140:141]
	global_load_lds_dwordx4 v[208:209], off
	s_add_i32 m0, s57, 0x2000
	v_lshl_add_u64 v[246:247], s[26:27], 0, v[144:145]
	global_load_lds_dwordx4 v[244:245], off
	s_mov_b32 m0, s38
	v_lshl_add_u64 v[248:249], s[26:27], 0, v[142:143]
	global_load_lds_dwordx4 v[246:247], off
	s_mov_b32 m0, s39
	s_nop 0
	global_load_lds_dwordx4 v[248:249], off
	s_cmp_eq_u32 s100, 0
	s_cbranch_scc1 .Lgw8_0_1
	s_cmp_eq_u32 s100, 8
	s_cbranch_scc1 .Lgw16_0_1
	s_waitcnt vmcnt(24)
	s_branch .Lgwd_0_1

.Lgwd_0_1:
	s_waitcnt lgkmcnt(0)
	s_barrier
	s_setprio 1
	s_waitcnt lgkmcnt(0)
	v_mfma_f32_16x16x32_bf16 v[60:63], v[150:153], v[186:189], v[60:63]
	v_mfma_f32_16x16x32_bf16 v[56:59], v[162:165], v[186:189], v[56:59]
	v_mfma_f32_16x16x32_bf16 v[44:47], v[150:153], v[194:197], v[44:47]
	v_mfma_f32_16x16x32_bf16 v[40:43], v[162:165], v[194:197], v[40:43]
	v_mfma_f32_16x16x32_bf16 v[28:31], v[150:153], v[224:227], v[28:31]
	v_mfma_f32_16x16x32_bf16 v[24:27], v[162:165], v[224:227], v[24:27]
	v_mfma_f32_16x16x32_bf16 v[12:15], v[150:153], v[232:235], v[12:15]
	v_mfma_f32_16x16x32_bf16 v[8:11], v[162:165], v[232:235], v[8:11]
	v_mfma_f32_16x16x32_bf16 v[60:63], v[158:161], v[190:193], v[60:63]
	v_mfma_f32_16x16x32_bf16 v[56:59], v[166:169], v[190:193], v[56:59]
	v_mfma_f32_16x16x32_bf16 v[44:47], v[158:161], v[220:223], v[44:47]
	v_mfma_f32_16x16x32_bf16 v[40:43], v[166:169], v[220:223], v[40:43]
	v_mfma_f32_16x16x32_bf16 v[28:31], v[158:161], v[228:231], v[28:31]
	v_mfma_f32_16x16x32_bf16 v[24:27], v[166:169], v[228:231], v[24:27]
	v_mfma_f32_16x16x32_bf16 v[12:15], v[158:161], v[236:239], v[12:15]
	v_mfma_f32_16x16x32_bf16 v[8:11], v[166:169], v[236:239], v[8:11]
	s_setprio 0
	s_setprio 1
	v_mfma_f32_16x16x32_bf16 v[52:55], v[170:173], v[186:189], v[52:55]
	v_mfma_f32_16x16x32_bf16 v[48:51], v[178:181], v[186:189], v[48:51]
	v_mfma_f32_16x16x32_bf16 v[36:39], v[170:173], v[194:197], v[36:39]
	v_mfma_f32_16x16x32_bf16 v[32:35], v[178:181], v[194:197], v[32:35]
	v_mfma_f32_16x16x32_bf16 v[20:23], v[170:173], v[224:227], v[20:23]
	v_mfma_f32_16x16x32_bf16 v[16:19], v[178:181], v[224:227], v[16:19]
	v_mfma_f32_16x16x32_bf16 v[4:7], v[170:173], v[232:235], v[4:7]
	v_mfma_f32_16x16x32_bf16 v[0:3], v[178:181], v[232:235], v[0:3]
	v_mfma_f32_16x16x32_bf16 v[52:55], v[174:177], v[190:193], v[52:55]
	v_mfma_f32_16x16x32_bf16 v[48:51], v[182:185], v[190:193], v[48:51]
	v_mfma_f32_16x16x32_bf16 v[36:39], v[174:177], v[220:223], v[36:39]
	v_mfma_f32_16x16x32_bf16 v[32:35], v[182:185], v[220:223], v[32:35]
	v_mfma_f32_16x16x32_bf16 v[20:23], v[174:177], v[228:231], v[20:23]
	v_mfma_f32_16x16x32_bf16 v[16:19], v[182:185], v[228:231], v[16:19]
	v_mfma_f32_16x16x32_bf16 v[4:7], v[174:177], v[236:239], v[4:7]
	v_mfma_f32_16x16x32_bf16 v[0:3], v[182:185], v[236:239], v[0:3]
	s_setprio 0
	s_barrier
	s_add_i32 s57, 16, 0x18000
	s_add_i32 s58, 16, 0x1c000
	v_add_u32_e32 v166, s57, v137
	v_add_u32_e32 v182, s58, v137
	ds_read_b128 v[150:153], v166
	ds_read_b128 v[158:161], v166 offset:1024
	ds_read_b128 v[162:165], v166 offset:2048
	ds_read_b128 v[166:169], v166 offset:3072
	ds_read_b128 v[170:173], v182
	ds_read_b128 v[174:177], v182 offset:1024
	ds_read_b128 v[178:181], v182 offset:2048
	ds_read_b128 v[182:185], v182 offset:3072
	s_add_u32 s26, s26, s2
	s_addc_u32 s27, s27, s3
	s_mov_b32 m0, s44
	v_lshl_add_u64 v[250:251], s[26:27], 0, v[144:145]
	ds_read_b128 v[186:189], v157 offset:32768
	ds_read_b128 v[190:193], v157 offset:33792
	ds_read_b128 v[194:197], v157 offset:34816
	ds_read_b128 v[220:223], v157 offset:35840
	ds_read_b128 v[224:227], v157 offset:36864
	ds_read_b128 v[228:231], v157 offset:37888
	ds_read_b128 v[232:235], v157 offset:38912
	ds_read_b128 v[236:239], v157 offset:39936
	global_load_lds_dwordx4 v[250:251], off
	v_lshl_add_u64 v[250:251], s[26:27], 0, v[142:143]
	s_mov_b32 m0, s45
	s_nop 0
	global_load_lds_dwordx4 v[250:251], off
	s_waitcnt vmcnt(8)
	s_waitcnt lgkmcnt(0)
	s_barrier
	s_setprio 1
	s_waitcnt lgkmcnt(0)
	v_mfma_f32_16x16x32_bf16 v[120:123], v[150:153], v[186:189], v[120:123]
	v_mfma_f32_16x16x32_bf16 v[124:127], v[162:165], v[186:189], v[124:127]
	v_mfma_f32_16x16x32_bf16 v[108:111], v[150:153], v[194:197], v[108:111]
	v_mfma_f32_16x16x32_bf16 v[104:107], v[162:165], v[194:197], v[104:107]
	v_mfma_f32_16x16x32_bf16 v[92:95], v[150:153], v[224:227], v[92:95]
	v_mfma_f32_16x16x32_bf16 v[88:91], v[162:165], v[224:227], v[88:91]
	v_mfma_f32_16x16x32_bf16 v[76:79], v[150:153], v[232:235], v[76:79]
	v_mfma_f32_16x16x32_bf16 v[72:75], v[162:165], v[232:235], v[72:75]
	v_mfma_f32_16x16x32_bf16 v[120:123], v[158:161], v[190:193], v[120:123]
	v_mfma_f32_16x16x32_bf16 v[124:127], v[166:169], v[190:193], v[124:127]
	v_mfma_f32_16x16x32_bf16 v[108:111], v[158:161], v[220:223], v[108:111]
	v_mfma_f32_16x16x32_bf16 v[104:107], v[166:169], v[220:223], v[104:107]
	v_mfma_f32_16x16x32_bf16 v[92:95], v[158:161], v[228:231], v[92:95]
	v_mfma_f32_16x16x32_bf16 v[88:91], v[166:169], v[228:231], v[88:91]
	v_mfma_f32_16x16x32_bf16 v[76:79], v[158:161], v[236:239], v[76:79]
	v_mfma_f32_16x16x32_bf16 v[72:75], v[166:169], v[236:239], v[72:75]
	s_setprio 0
	s_setprio 1
	v_mfma_f32_16x16x32_bf16 v[116:119], v[170:173], v[186:189], v[116:119]
	v_mfma_f32_16x16x32_bf16 v[112:115], v[178:181], v[186:189], v[112:115]
	v_mfma_f32_16x16x32_bf16 v[100:103], v[170:173], v[194:197], v[100:103]
	v_mfma_f32_16x16x32_bf16 v[96:99], v[178:181], v[194:197], v[96:99]
	v_mfma_f32_16x16x32_bf16 v[84:87], v[170:173], v[224:227], v[84:87]
	v_mfma_f32_16x16x32_bf16 v[80:83], v[178:181], v[224:227], v[80:83]
	v_mfma_f32_16x16x32_bf16 v[68:71], v[170:173], v[232:235], v[68:71]
	v_mfma_f32_16x16x32_bf16 v[64:67], v[178:181], v[232:235], v[64:67]
	v_mfma_f32_16x16x32_bf16 v[116:119], v[174:177], v[190:193], v[116:119]
	v_mfma_f32_16x16x32_bf16 v[112:115], v[182:185], v[190:193], v[112:115]
	v_mfma_f32_16x16x32_bf16 v[100:103], v[174:177], v[220:223], v[100:103]
	v_mfma_f32_16x16x32_bf16 v[96:99], v[182:185], v[220:223], v[96:99]
	v_mfma_f32_16x16x32_bf16 v[84:87], v[174:177], v[228:231], v[84:87]
	v_mfma_f32_16x16x32_bf16 v[80:83], v[182:185], v[228:231], v[80:83]
	v_mfma_f32_16x16x32_bf16 v[68:71], v[174:177], v[236:239], v[68:71]
	v_mfma_f32_16x16x32_bf16 v[64:67], v[182:185], v[236:239], v[64:67]
	s_setprio 0
	s_barrier
	s_add_i32 s26, s57, s35
	v_lshl_add_u64 v[154:155], v[154:155], 0, s[98:99]
	s_mov_b32 m0, s26
	ds_read_b128 v[186:189], v157 offset:49152
	ds_read_b128 v[190:193], v157 offset:50176
	ds_read_b128 v[194:197], v157 offset:51200
	ds_read_b128 v[220:223], v157 offset:52224
	ds_read_b128 v[224:227], v157 offset:53248
	ds_read_b128 v[228:231], v157 offset:54272
	ds_read_b128 v[232:235], v157 offset:55296
	ds_read_b128 v[236:239], v157 offset:56320
	global_load_lds_dwordx4 v[154:155], off
	v_lshl_add_u64 v[154:155], v[198:199], 0, s[98:99]
	s_add_i32 m0, s26, 0x2000
	s_add_i32 s26, s58, s35
	global_load_lds_dwordx4 v[154:155], off
	v_lshl_add_u64 v[154:155], v[208:209], 0, s[98:99]
	s_mov_b32 m0, s26
	s_nop 0
	global_load_lds_dwordx4 v[154:155], off
	v_lshl_add_u64 v[154:155], v[244:245], 0, s[98:99]
	s_add_i32 m0, s26, 0x2000
	s_nop 0
	global_load_lds_dwordx4 v[154:155], off
	v_lshl_add_u64 v[154:155], v[246:247], 0, s[98:99]
	s_mov_b32 m0, s46
	s_nop 0
	global_load_lds_dwordx4 v[154:155], off
	v_lshl_add_u64 v[154:155], v[248:249], 0, s[98:99]
	s_mov_b32 m0, s47
	s_nop 0
	global_load_lds_dwordx4 v[154:155], off
	s_waitcnt vmcnt(8)
	s_waitcnt lgkmcnt(0)
	s_barrier
	s_setprio 1
	s_waitcnt lgkmcnt(0)
	v_mfma_f32_16x16x32_bf16 v[60:63], v[150:153], v[186:189], v[60:63]
	v_mfma_f32_16x16x32_bf16 v[56:59], v[162:165], v[186:189], v[56:59]
	v_mfma_f32_16x16x32_bf16 v[44:47], v[150:153], v[194:197], v[44:47]
	v_mfma_f32_16x16x32_bf16 v[40:43], v[162:165], v[194:197], v[40:43]
	v_mfma_f32_16x16x32_bf16 v[28:31], v[150:153], v[224:227], v[28:31]
	v_mfma_f32_16x16x32_bf16 v[24:27], v[162:165], v[224:227], v[24:27]
	v_mfma_f32_16x16x32_bf16 v[12:15], v[150:153], v[232:235], v[12:15]
	v_mfma_f32_16x16x32_bf16 v[8:11], v[162:165], v[232:235], v[8:11]
	v_mfma_f32_16x16x32_bf16 v[60:63], v[158:161], v[190:193], v[60:63]
	v_mfma_f32_16x16x32_bf16 v[56:59], v[166:169], v[190:193], v[56:59]
	v_mfma_f32_16x16x32_bf16 v[44:47], v[158:161], v[220:223], v[44:47]
	v_mfma_f32_16x16x32_bf16 v[40:43], v[166:169], v[220:223], v[40:43]
	v_mfma_f32_16x16x32_bf16 v[28:31], v[158:161], v[228:231], v[28:31]
	v_mfma_f32_16x16x32_bf16 v[24:27], v[166:169], v[228:231], v[24:27]
	v_mfma_f32_16x16x32_bf16 v[12:15], v[158:161], v[236:239], v[12:15]
	v_mfma_f32_16x16x32_bf16 v[8:11], v[166:169], v[236:239], v[8:11]
	s_setprio 0
	s_setprio 1
	v_mfma_f32_16x16x32_bf16 v[52:55], v[170:173], v[186:189], v[52:55]
	v_mfma_f32_16x16x32_bf16 v[48:51], v[178:181], v[186:189], v[48:51]
	v_mfma_f32_16x16x32_bf16 v[36:39], v[170:173], v[194:197], v[36:39]
	v_mfma_f32_16x16x32_bf16 v[32:35], v[178:181], v[194:197], v[32:35]
	v_mfma_f32_16x16x32_bf16 v[20:23], v[170:173], v[224:227], v[20:23]
	v_mfma_f32_16x16x32_bf16 v[16:19], v[178:181], v[224:227], v[16:19]
	v_mfma_f32_16x16x32_bf16 v[4:7], v[170:173], v[232:235], v[4:7]
	v_mfma_f32_16x16x32_bf16 v[0:3], v[178:181], v[232:235], v[0:3]
	v_mfma_f32_16x16x32_bf16 v[52:55], v[174:177], v[190:193], v[52:55]
	v_mfma_f32_16x16x32_bf16 v[48:51], v[182:185], v[190:193], v[48:51]
	v_mfma_f32_16x16x32_bf16 v[36:39], v[174:177], v[220:223], v[36:39]
	v_mfma_f32_16x16x32_bf16 v[32:35], v[182:185], v[220:223], v[32:35]
	v_mfma_f32_16x16x32_bf16 v[20:23], v[174:177], v[228:231], v[20:23]
	v_mfma_f32_16x16x32_bf16 v[16:19], v[182:185], v[228:231], v[16:19]
	v_mfma_f32_16x16x32_bf16 v[4:7], v[174:177], v[236:239], v[4:7]
	v_mfma_f32_16x16x32_bf16 v[0:3], v[182:185], v[236:239], v[0:3]
	s_setprio 0
	s_barrier
	s_add_u32 s0, s0, 0x100
	s_addc_u32 s1, s1, 0
	s_add_u32 s28, s28, 0x100
	s_addc_u32 s29, s29, 0
	s_cmp_ge_i32 s56, s48
	s_mov_b32 s26, s56
	s_cbranch_scc0 .LBB0_47
	v_readlane_b32 s58, v255, 20
	v_readlane_b32 s59, v255, 21
	s_mov_b32 s60, 0xec801000

.LBB0_51:
	s_mov_b32 s101, 16
	v_lshl_add_u32 v152, s55, 8, v135
	v_ashrrev_i32_e32 v153, 31, v152
	v_lshl_or_b32 v150, s54, 8, v156
	v_lshlrev_b64 v[154:155], 11, v[152:153]
	v_ashrrev_i32_e32 v151, 31, v150
	v_lshl_add_u64 v[154:155], s[8:9], 0, v[154:155]
	s_movk_i32 s0, 0x400
	v_lshl_add_u64 v[154:155], v[150:151], 1, v[154:155]
	v_cmp_gt_i32_e32 vcc, s0, v150
	s_and_saveexec_b64 s[0:1], vcc
	s_cbranch_execz .LBB0_53
	v_cvt_pk_bf16_f32 v120, v120, v121
	v_cvt_pk_bf16_f32 v121, v122, v123
	v_cvt_pk_bf16_f32 v122, v124, v125
	v_cvt_pk_bf16_f32 v123, v126, v127
	global_store_dwordx4 v[154:155], v[120:123], off

.LBB0_92:
	s_add_i32 m0, s36, 0x18000
	v_lshl_add_u64 v[0:1], v[0:1], 0, s[98:99]
	s_waitcnt vmcnt(2)
	s_barrier
	global_load_lds_dwordx4 v[0:1], off
	v_lshl_add_u64 v[0:1], v[2:3], 0, s[98:99]
	s_add_i32 m0, s36, 0x1a000
	s_add_i32 s44, s36, 0x8000
	global_load_lds_dwordx4 v[0:1], off
	v_lshl_add_u64 v[0:1], v[8:9], 0, s[98:99]
	s_mov_b32 m0, s44
	s_add_i32 s45, s36, 0xa000
	global_load_lds_dwordx4 v[0:1], off
	v_lshl_add_u64 v[0:1], v[10:11], 0, s[98:99]
	s_mov_b32 m0, s45
	v_readlane_b32 s16, v255, 23
	global_load_lds_dwordx4 v[0:1], off
	s_add_i32 m0, s36, 0x1c000
	v_lshl_add_u64 v[0:1], v[4:5], 0, s[98:99]
	global_load_lds_dwordx4 v[0:1], off
	v_lshl_add_u64 v[0:1], v[6:7], 0, s[98:99]
	s_add_i32 m0, s36, 0x1e000
	v_readlane_b32 s17, v255, 24
	global_load_lds_dwordx4 v[0:1], off
	v_lshrrev_b32_e32 v1, 1, v12
	v_and_b32_e32 v1, 24, v1
	v_and_b32_e32 v0, 15, v12
	v_lshlrev_b32_e32 v2, 1, v1
	v_lshl_or_b32 v135, s14, 6, v0
	v_lshl_or_b32 v0, v0, 6, v2
	v_lshlrev_b32_e32 v2, 2, v12
	s_lshl_b32 s1, s1, 5
	s_lshr_b32 s15, s17, 26
	s_lshl_b32 s14, s14, 13
	v_and_b32_e32 v2, 32, v2
	s_and_b32 s1, s1, 0x60
	s_add_i32 s15, s16, s15
	v_bitop3_b32 v3, v0, s14, v2 bitop3:0xde
	s_lshl_b32 s14, s1, 7
	s_ashr_i32 s46, s15, 6
	v_bitop3_b32 v137, v0, s14, v2 bitop3:0xde
	v_add_u32_e32 v0, v18, v16
	s_cmp_gt_i32 s16, 63
	v_or_b32_e32 v152, s1, v1
	v_add_lshl_u32 v0, v0, v17, 1
	v_mov_b32_e32 v1, v129
	s_waitcnt vmcnt(6)
	s_cselect_b64 s[14:15], -1, 0
	s_add_i32 s47, s46, -2
	v_lshl_add_u64 v[146:147], s[2:3], 0, v[0:1]
	v_add_u32_e32 v0, v15, v13
	s_cmpk_lt_u32 s0, 0x100
	v_add_lshl_u32 v0, v0, v14, 1
	s_cselect_b64 s[16:17], -1, 0
	s_waitcnt lgkmcnt(0)
	s_ashr_i32 s48, s28, 31
	v_lshl_add_u64 v[148:149], s[2:3], 0, v[0:1]
	s_mov_b32 s49, 0
	v_add_u32_e32 v153, 16, v3
	v_readlane_b32 s52, v253, 20
	v_readlane_b32 s53, v253, 21
	s_barrier
	s_mov_b32 s101, 0
	s_branch .LBB0_95

.LBB0_103:
	s_cmp_eq_u32 s26, 0
	s_cselect_b32 s100, s101, 0
	s_add_i32 s56, s26, 2
	s_add_u32 s57, s24, 0x80
	s_addc_u32 s27, s25, 0
	s_add_i32 s60, 16, 0x10000
	s_cmp_eq_u32 s47, s26
	s_cselect_b32 s27, s1, s27
	s_cselect_b32 s26, s0, s57
	v_add_u32_e32 v150, s60, v137
	s_cselect_b32 s59, s21, s55
	s_cselect_b32 s58, s20, s54
	s_add_i32 s57, 16, 0x14000
	ds_read_b128 v[154:157], v150
	ds_read_b128 v[158:161], v150 offset:1024
	ds_read_b128 v[162:165], v150 offset:2048
	ds_read_b128 v[166:169], v150 offset:3072
	v_add_u32_e32 v150, s57, v137
	ds_read_b128 v[170:173], v150
	ds_read_b128 v[174:177], v150 offset:1024
	ds_read_b128 v[178:181], v150 offset:2048
	ds_read_b128 v[182:185], v150 offset:3072
	v_lshl_add_u64 v[150:151], s[24:25], 0, v[146:147]
	s_add_i32 m0, s36, 0xc000
	ds_read_b128 v[186:189], v153
	ds_read_b128 v[190:193], v153 offset:1024
	ds_read_b128 v[194:197], v153 offset:2048
	ds_read_b128 v[220:223], v153 offset:3072
	ds_read_b128 v[224:227], v153 offset:4096
	ds_read_b128 v[228:231], v153 offset:5120
	ds_read_b128 v[232:235], v153 offset:6144
	ds_read_b128 v[236:239], v153 offset:7168
	global_load_lds_dwordx4 v[150:151], off
	v_lshl_add_u64 v[150:151], s[24:25], 0, v[148:149]
	s_add_i32 m0, s36, 0xe000
	s_nop 0
	global_load_lds_dwordx4 v[150:151], off
	s_cmp_eq_u32 s100, 0
	s_cbranch_scc1 .Lgw8_1_0
	s_cmp_eq_u32 s100, 8
	s_cbranch_scc1 .Lgw16_1_0
	s_waitcnt vmcnt(24)
	s_branch .Lgwd_1_0

.Lgwd_1_0:
	s_waitcnt lgkmcnt(0)
	s_barrier
	s_setprio 1
	s_waitcnt lgkmcnt(0)
	v_mfma_f32_16x16x32_bf16 v[124:127], v[154:157], v[186:189], v[124:127]
	v_mfma_f32_16x16x32_bf16 v[116:119], v[162:165], v[186:189], v[116:119]
	v_mfma_f32_16x16x32_bf16 v[108:111], v[154:157], v[194:197], v[108:111]
	v_mfma_f32_16x16x32_bf16 v[100:103], v[162:165], v[194:197], v[100:103]
	v_mfma_f32_16x16x32_bf16 v[92:95], v[154:157], v[224:227], v[92:95]
	v_mfma_f32_16x16x32_bf16 v[84:87], v[162:165], v[224:227], v[84:87]
	v_mfma_f32_16x16x32_bf16 v[76:79], v[154:157], v[232:235], v[76:79]
	v_mfma_f32_16x16x32_bf16 v[68:71], v[162:165], v[232:235], v[68:71]
	v_mfma_f32_16x16x32_bf16 v[124:127], v[158:161], v[190:193], v[124:127]
	v_mfma_f32_16x16x32_bf16 v[116:119], v[166:169], v[190:193], v[116:119]
	v_mfma_f32_16x16x32_bf16 v[108:111], v[158:161], v[220:223], v[108:111]
	v_mfma_f32_16x16x32_bf16 v[100:103], v[166:169], v[220:223], v[100:103]
	v_mfma_f32_16x16x32_bf16 v[92:95], v[158:161], v[228:231], v[92:95]
	v_mfma_f32_16x16x32_bf16 v[84:87], v[166:169], v[228:231], v[84:87]
	v_mfma_f32_16x16x32_bf16 v[76:79], v[158:161], v[236:239], v[76:79]
	v_mfma_f32_16x16x32_bf16 v[68:71], v[166:169], v[236:239], v[68:71]
	s_setprio 0
	s_setprio 1
	v_mfma_f32_16x16x32_bf16 v[120:123], v[170:173], v[186:189], v[120:123]
	v_mfma_f32_16x16x32_bf16 v[112:115], v[178:181], v[186:189], v[112:115]
	v_mfma_f32_16x16x32_bf16 v[104:107], v[170:173], v[194:197], v[104:107]
	v_mfma_f32_16x16x32_bf16 v[96:99], v[178:181], v[194:197], v[96:99]
	v_mfma_f32_16x16x32_bf16 v[88:91], v[170:173], v[224:227], v[88:91]
	v_mfma_f32_16x16x32_bf16 v[80:83], v[178:181], v[224:227], v[80:83]
	v_mfma_f32_16x16x32_bf16 v[72:75], v[170:173], v[232:235], v[72:75]
	v_mfma_f32_16x16x32_bf16 v[64:67], v[178:181], v[232:235], v[64:67]
	v_mfma_f32_16x16x32_bf16 v[120:123], v[174:177], v[190:193], v[120:123]
	v_mfma_f32_16x16x32_bf16 v[112:115], v[182:185], v[190:193], v[112:115]
	v_mfma_f32_16x16x32_bf16 v[104:107], v[174:177], v[220:223], v[104:107]
	v_mfma_f32_16x16x32_bf16 v[96:99], v[182:185], v[220:223], v[96:99]
	v_mfma_f32_16x16x32_bf16 v[88:91], v[174:177], v[228:231], v[88:91]
	v_mfma_f32_16x16x32_bf16 v[80:83], v[182:185], v[228:231], v[80:83]
	v_mfma_f32_16x16x32_bf16 v[72:75], v[174:177], v[236:239], v[72:75]
	v_mfma_f32_16x16x32_bf16 v[64:67], v[182:185], v[236:239], v[64:67]
	s_setprio 0
	s_barrier
	s_add_i32 s60, s60, s29
	v_lshl_add_u64 v[150:151], s[58:59], 0, v[128:129]
	s_mov_b32 m0, s60
	ds_read_b128 v[186:189], v153 offset:16384
	ds_read_b128 v[190:193], v153 offset:17408
	ds_read_b128 v[194:197], v153 offset:18432
	ds_read_b128 v[220:223], v153 offset:19456
	ds_read_b128 v[224:227], v153 offset:20480
	ds_read_b128 v[228:231], v153 offset:21504
	ds_read_b128 v[232:235], v153 offset:22528
	ds_read_b128 v[236:239], v153 offset:23552
	global_load_lds_dwordx4 v[150:151], off
	s_add_i32 m0, s60, 0x2000
	v_lshl_add_u64 v[198:199], s[58:59], 0, v[140:141]
	s_add_u32 s58, s58, s2
	s_addc_u32 s59, s59, s3
	s_add_i32 s57, s57, s29
	global_load_lds_dwordx4 v[198:199], off
	v_lshl_add_u64 v[208:209], s[58:59], 0, v[128:129]
	s_mov_b32 m0, s57
	v_lshl_add_u64 v[244:245], s[58:59], 0, v[140:141]
	global_load_lds_dwordx4 v[208:209], off
	s_add_i32 m0, s57, 0x2000
	v_lshl_add_u64 v[246:247], s[26:27], 0, v[144:145]
	global_load_lds_dwordx4 v[244:245], off
	s_mov_b32 m0, s36
	v_lshl_add_u64 v[248:249], s[26:27], 0, v[142:143]
	global_load_lds_dwordx4 v[246:247], off
	s_mov_b32 m0, s37
	s_nop 0
	global_load_lds_dwordx4 v[248:249], off
	s_cmp_eq_u32 s100, 0
	s_cbranch_scc1 .Lgw8_1_1
	s_cmp_eq_u32 s100, 8
	s_cbranch_scc1 .Lgw16_1_1
	s_waitcnt vmcnt(24)
	s_branch .Lgwd_1_1

.Lgwd_1_1:
	s_waitcnt lgkmcnt(0)
	s_barrier
	s_setprio 1
	s_waitcnt lgkmcnt(0)
	v_mfma_f32_16x16x32_bf16 v[60:63], v[154:157], v[186:189], v[60:63]
	v_mfma_f32_16x16x32_bf16 v[52:55], v[162:165], v[186:189], v[52:55]
	v_mfma_f32_16x16x32_bf16 v[44:47], v[154:157], v[194:197], v[44:47]
	v_mfma_f32_16x16x32_bf16 v[36:39], v[162:165], v[194:197], v[36:39]
	v_mfma_f32_16x16x32_bf16 v[28:31], v[154:157], v[224:227], v[28:31]
	v_mfma_f32_16x16x32_bf16 v[20:23], v[162:165], v[224:227], v[20:23]
	v_mfma_f32_16x16x32_bf16 v[12:15], v[154:157], v[232:235], v[12:15]
	v_mfma_f32_16x16x32_bf16 v[4:7], v[162:165], v[232:235], v[4:7]
	v_mfma_f32_16x16x32_bf16 v[60:63], v[158:161], v[190:193], v[60:63]
	v_mfma_f32_16x16x32_bf16 v[52:55], v[166:169], v[190:193], v[52:55]
	v_mfma_f32_16x16x32_bf16 v[44:47], v[158:161], v[220:223], v[44:47]
	v_mfma_f32_16x16x32_bf16 v[36:39], v[166:169], v[220:223], v[36:39]
	v_mfma_f32_16x16x32_bf16 v[28:31], v[158:161], v[228:231], v[28:31]
	v_mfma_f32_16x16x32_bf16 v[20:23], v[166:169], v[228:231], v[20:23]
	v_mfma_f32_16x16x32_bf16 v[12:15], v[158:161], v[236:239], v[12:15]
	v_mfma_f32_16x16x32_bf16 v[4:7], v[166:169], v[236:239], v[4:7]
	s_setprio 0
	s_setprio 1
	v_mfma_f32_16x16x32_bf16 v[56:59], v[170:173], v[186:189], v[56:59]
	v_mfma_f32_16x16x32_bf16 v[48:51], v[178:181], v[186:189], v[48:51]
	v_mfma_f32_16x16x32_bf16 v[40:43], v[170:173], v[194:197], v[40:43]
	v_mfma_f32_16x16x32_bf16 v[32:35], v[178:181], v[194:197], v[32:35]
	v_mfma_f32_16x16x32_bf16 v[24:27], v[170:173], v[224:227], v[24:27]
	v_mfma_f32_16x16x32_bf16 v[16:19], v[178:181], v[224:227], v[16:19]
	v_mfma_f32_16x16x32_bf16 v[8:11], v[170:173], v[232:235], v[8:11]
	v_mfma_f32_16x16x32_bf16 v[0:3], v[178:181], v[232:235], v[0:3]
	v_mfma_f32_16x16x32_bf16 v[56:59], v[174:177], v[190:193], v[56:59]
	v_mfma_f32_16x16x32_bf16 v[48:51], v[182:185], v[190:193], v[48:51]
	v_mfma_f32_16x16x32_bf16 v[40:43], v[174:177], v[220:223], v[40:43]
	v_mfma_f32_16x16x32_bf16 v[32:35], v[182:185], v[220:223], v[32:35]
	v_mfma_f32_16x16x32_bf16 v[24:27], v[174:177], v[228:231], v[24:27]
	v_mfma_f32_16x16x32_bf16 v[16:19], v[182:185], v[228:231], v[16:19]
	v_mfma_f32_16x16x32_bf16 v[8:11], v[174:177], v[236:239], v[8:11]
	v_mfma_f32_16x16x32_bf16 v[0:3], v[182:185], v[236:239], v[0:3]
	s_setprio 0
	s_barrier
	s_add_i32 s57, 16, 0x18000
	s_add_i32 s58, 16, 0x1c000
	v_add_u32_e32 v166, s57, v137
	v_add_u32_e32 v182, s58, v137
	ds_read_b128 v[154:157], v166
	ds_read_b128 v[158:161], v166 offset:1024
	ds_read_b128 v[162:165], v166 offset:2048
	ds_read_b128 v[166:169], v166 offset:3072
	ds_read_b128 v[170:173], v182
	ds_read_b128 v[174:177], v182 offset:1024
	ds_read_b128 v[178:181], v182 offset:2048
	ds_read_b128 v[182:185], v182 offset:3072
	s_add_u32 s26, s26, s2
	s_addc_u32 s27, s27, s3
	s_mov_b32 m0, s38
	v_lshl_add_u64 v[250:251], s[26:27], 0, v[144:145]
	ds_read_b128 v[186:189], v153 offset:32768
	ds_read_b128 v[190:193], v153 offset:33792
	ds_read_b128 v[194:197], v153 offset:34816
	ds_read_b128 v[220:223], v153 offset:35840
	ds_read_b128 v[224:227], v153 offset:36864
	ds_read_b128 v[228:231], v153 offset:37888
	ds_read_b128 v[232:235], v153 offset:38912
	ds_read_b128 v[236:239], v153 offset:39936
	global_load_lds_dwordx4 v[250:251], off
	v_lshl_add_u64 v[250:251], s[26:27], 0, v[142:143]
	s_mov_b32 m0, s39
	s_nop 0
	global_load_lds_dwordx4 v[250:251], off
	s_waitcnt vmcnt(8)
	s_waitcnt lgkmcnt(0)
	s_barrier
	s_setprio 1
	s_waitcnt lgkmcnt(0)
	v_mfma_f32_16x16x32_bf16 v[124:127], v[154:157], v[186:189], v[124:127]
	v_mfma_f32_16x16x32_bf16 v[116:119], v[162:165], v[186:189], v[116:119]
	v_mfma_f32_16x16x32_bf16 v[108:111], v[154:157], v[194:197], v[108:111]
	v_mfma_f32_16x16x32_bf16 v[100:103], v[162:165], v[194:197], v[100:103]
	v_mfma_f32_16x16x32_bf16 v[92:95], v[154:157], v[224:227], v[92:95]
	v_mfma_f32_16x16x32_bf16 v[84:87], v[162:165], v[224:227], v[84:87]
	v_mfma_f32_16x16x32_bf16 v[76:79], v[154:157], v[232:235], v[76:79]
	v_mfma_f32_16x16x32_bf16 v[68:71], v[162:165], v[232:235], v[68:71]
	v_mfma_f32_16x16x32_bf16 v[124:127], v[158:161], v[190:193], v[124:127]
	v_mfma_f32_16x16x32_bf16 v[116:119], v[166:169], v[190:193], v[116:119]
	v_mfma_f32_16x16x32_bf16 v[108:111], v[158:161], v[220:223], v[108:111]
	v_mfma_f32_16x16x32_bf16 v[100:103], v[166:169], v[220:223], v[100:103]
	v_mfma_f32_16x16x32_bf16 v[92:95], v[158:161], v[228:231], v[92:95]
	v_mfma_f32_16x16x32_bf16 v[84:87], v[166:169], v[228:231], v[84:87]
	v_mfma_f32_16x16x32_bf16 v[76:79], v[158:161], v[236:239], v[76:79]
	v_mfma_f32_16x16x32_bf16 v[68:71], v[166:169], v[236:239], v[68:71]
	s_setprio 0
	s_setprio 1
	v_mfma_f32_16x16x32_bf16 v[120:123], v[170:173], v[186:189], v[120:123]
	v_mfma_f32_16x16x32_bf16 v[112:115], v[178:181], v[186:189], v[112:115]
	v_mfma_f32_16x16x32_bf16 v[104:107], v[170:173], v[194:197], v[104:107]
	v_mfma_f32_16x16x32_bf16 v[96:99], v[178:181], v[194:197], v[96:99]
	v_mfma_f32_16x16x32_bf16 v[88:91], v[170:173], v[224:227], v[88:91]
	v_mfma_f32_16x16x32_bf16 v[80:83], v[178:181], v[224:227], v[80:83]
	v_mfma_f32_16x16x32_bf16 v[72:75], v[170:173], v[232:235], v[72:75]
	v_mfma_f32_16x16x32_bf16 v[64:67], v[178:181], v[232:235], v[64:67]
	v_mfma_f32_16x16x32_bf16 v[120:123], v[174:177], v[190:193], v[120:123]
	v_mfma_f32_16x16x32_bf16 v[112:115], v[182:185], v[190:193], v[112:115]
	v_mfma_f32_16x16x32_bf16 v[104:107], v[174:177], v[220:223], v[104:107]
	v_mfma_f32_16x16x32_bf16 v[96:99], v[182:185], v[220:223], v[96:99]
	v_mfma_f32_16x16x32_bf16 v[88:91], v[174:177], v[228:231], v[88:91]
	v_mfma_f32_16x16x32_bf16 v[80:83], v[182:185], v[228:231], v[80:83]
	v_mfma_f32_16x16x32_bf16 v[72:75], v[174:177], v[236:239], v[72:75]
	v_mfma_f32_16x16x32_bf16 v[64:67], v[182:185], v[236:239], v[64:67]
	s_setprio 0
	s_barrier
	s_add_i32 s26, s57, s29
	v_lshl_add_u64 v[150:151], v[150:151], 0, s[98:99]
	s_mov_b32 m0, s26
	ds_read_b128 v[186:189], v153 offset:49152
	ds_read_b128 v[190:193], v153 offset:50176
	ds_read_b128 v[194:197], v153 offset:51200
	ds_read_b128 v[220:223], v153 offset:52224
	ds_read_b128 v[224:227], v153 offset:53248
	ds_read_b128 v[228:231], v153 offset:54272
	ds_read_b128 v[232:235], v153 offset:55296
	ds_read_b128 v[236:239], v153 offset:56320
	global_load_lds_dwordx4 v[150:151], off
	v_lshl_add_u64 v[150:151], v[198:199], 0, s[98:99]
	s_add_i32 m0, s26, 0x2000
	s_add_i32 s26, s58, s29
	global_load_lds_dwordx4 v[150:151], off
	v_lshl_add_u64 v[150:151], v[208:209], 0, s[98:99]
	s_mov_b32 m0, s26
	s_nop 0
	global_load_lds_dwordx4 v[150:151], off
	v_lshl_add_u64 v[150:151], v[244:245], 0, s[98:99]
	s_add_i32 m0, s26, 0x2000
	s_nop 0
	global_load_lds_dwordx4 v[150:151], off
	v_lshl_add_u64 v[150:151], v[246:247], 0, s[98:99]
	s_mov_b32 m0, s44
	s_nop 0
	global_load_lds_dwordx4 v[150:151], off
	v_lshl_add_u64 v[150:151], v[248:249], 0, s[98:99]
	s_mov_b32 m0, s45
	s_nop 0
	global_load_lds_dwordx4 v[150:151], off
	s_waitcnt vmcnt(8)
	s_waitcnt lgkmcnt(0)
	s_barrier
	s_setprio 1
	s_waitcnt lgkmcnt(0)
	v_mfma_f32_16x16x32_bf16 v[60:63], v[154:157], v[186:189], v[60:63]
	v_mfma_f32_16x16x32_bf16 v[52:55], v[162:165], v[186:189], v[52:55]
	v_mfma_f32_16x16x32_bf16 v[44:47], v[154:157], v[194:197], v[44:47]
	v_mfma_f32_16x16x32_bf16 v[36:39], v[162:165], v[194:197], v[36:39]
	v_mfma_f32_16x16x32_bf16 v[28:31], v[154:157], v[224:227], v[28:31]
	v_mfma_f32_16x16x32_bf16 v[20:23], v[162:165], v[224:227], v[20:23]
	v_mfma_f32_16x16x32_bf16 v[12:15], v[154:157], v[232:235], v[12:15]
	v_mfma_f32_16x16x32_bf16 v[4:7], v[162:165], v[232:235], v[4:7]
	v_mfma_f32_16x16x32_bf16 v[60:63], v[158:161], v[190:193], v[60:63]
	v_mfma_f32_16x16x32_bf16 v[52:55], v[166:169], v[190:193], v[52:55]
	v_mfma_f32_16x16x32_bf16 v[44:47], v[158:161], v[220:223], v[44:47]
	v_mfma_f32_16x16x32_bf16 v[36:39], v[166:169], v[220:223], v[36:39]
	v_mfma_f32_16x16x32_bf16 v[28:31], v[158:161], v[228:231], v[28:31]
	v_mfma_f32_16x16x32_bf16 v[20:23], v[166:169], v[228:231], v[20:23]
	v_mfma_f32_16x16x32_bf16 v[12:15], v[158:161], v[236:239], v[12:15]
	v_mfma_f32_16x16x32_bf16 v[4:7], v[166:169], v[236:239], v[4:7]
	s_setprio 0
	s_setprio 1
	v_mfma_f32_16x16x32_bf16 v[56:59], v[170:173], v[186:189], v[56:59]
	v_mfma_f32_16x16x32_bf16 v[48:51], v[178:181], v[186:189], v[48:51]
	v_mfma_f32_16x16x32_bf16 v[40:43], v[170:173], v[194:197], v[40:43]
	v_mfma_f32_16x16x32_bf16 v[32:35], v[178:181], v[194:197], v[32:35]
	v_mfma_f32_16x16x32_bf16 v[24:27], v[170:173], v[224:227], v[24:27]
	v_mfma_f32_16x16x32_bf16 v[16:19], v[178:181], v[224:227], v[16:19]
	v_mfma_f32_16x16x32_bf16 v[8:11], v[170:173], v[232:235], v[8:11]
	v_mfma_f32_16x16x32_bf16 v[0:3], v[178:181], v[232:235], v[0:3]
	v_mfma_f32_16x16x32_bf16 v[56:59], v[174:177], v[190:193], v[56:59]
	v_mfma_f32_16x16x32_bf16 v[48:51], v[182:185], v[190:193], v[48:51]
	v_mfma_f32_16x16x32_bf16 v[40:43], v[174:177], v[220:223], v[40:43]
	v_mfma_f32_16x16x32_bf16 v[32:35], v[182:185], v[220:223], v[32:35]
	v_mfma_f32_16x16x32_bf16 v[24:27], v[174:177], v[228:231], v[24:27]
	v_mfma_f32_16x16x32_bf16 v[16:19], v[182:185], v[228:231], v[16:19]
	v_mfma_f32_16x16x32_bf16 v[8:11], v[174:177], v[236:239], v[8:11]
	v_mfma_f32_16x16x32_bf16 v[0:3], v[182:185], v[236:239], v[0:3]
	s_setprio 0
	s_barrier
	s_add_u32 s24, s24, 0x100
	s_addc_u32 s25, s25, 0
	s_add_u32 s54, s54, 0x100
	s_addc_u32 s55, s55, 0
	s_cmp_ge_i32 s56, s46
	s_mov_b32 s26, s56
	s_cbranch_scc0 .LBB0_103
	v_readlane_b32 s58, v255, 20
	v_readlane_b32 s59, v255, 21
	s_mov_b32 s60, 0xec801000

.LBB0_107:
	s_mov_b32 s101, 8
	v_mul_f32_e32 v150, 0xbfb8aa3b, v124
	v_exp_f32_e32 v150, v150
	v_mul_f32_e32 v151, 0xbfb8aa3b, v125
	v_exp_f32_e32 v151, v151
	v_mul_f32_e32 v155, 0xbfb8aa3b, v126
	v_add_f32_e32 v150, 1.0, v150
	v_rcp_f32_e32 v158, v150
	v_add_f32_e32 v150, 1.0, v151
	v_rcp_f32_e32 v159, v150
	v_exp_f32_e32 v155, v155
	v_lshl_or_b32 v156, s52, 7, v152
	v_lshl_add_u32 v154, s53, 8, v135
	v_pk_mul_f32 v[124:125], v[124:125], v[158:159]
	v_mul_f32_e32 v158, 0xbfb8aa3b, v127
	v_exp_f32_e32 v158, v158
	v_pk_mul_f32 v[120:121], v[120:121], v[124:125]
	v_add_f32_e32 v124, 1.0, v155
	v_mul_f32_e32 v155, 0xbfb8aa3b, v116
	v_add_f32_e32 v125, 1.0, v158
	v_rcp_f32_e32 v124, v124
	v_rcp_f32_e32 v125, v125
	v_exp_f32_e32 v155, v155
	v_mul_f32_e32 v158, 0xbfb8aa3b, v117
	v_exp_f32_e32 v158, v158
	v_pk_mul_f32 v[124:125], v[126:127], v[124:125]
	v_add_f32_e32 v126, 1.0, v155
	v_mul_f32_e32 v155, 0xbfb8aa3b, v118
	v_add_f32_e32 v127, 1.0, v158
	v_exp_f32_e32 v155, v155
	v_mul_f32_e32 v158, 0xbfb8aa3b, v119
	v_exp_f32_e32 v159, v158
	v_rcp_f32_e32 v126, v126
	v_add_f32_e32 v155, 1.0, v155
	v_rcp_f32_e32 v127, v127
	v_rcp_f32_e32 v158, v155
	v_add_f32_e32 v155, 1.0, v159
	v_rcp_f32_e32 v159, v155
	v_pk_mul_f32 v[116:117], v[116:117], v[126:127]
	v_ashrrev_i32_e32 v157, 31, v156
	v_pk_mul_f32 v[116:117], v[112:113], v[116:117]
	v_pk_mul_f32 v[112:113], v[118:119], v[158:159]
	v_cvt_pk_bf16_f32 v116, v116, v117
	v_pk_mul_f32 v[118:119], v[114:115], v[112:113]
	v_mov_b64_e32 v[150:151], s[22:23]
	v_cvt_pk_bf16_f32 v117, v118, v119
	v_mul_f32_e32 v118, 0xbfb8aa3b, v108
	v_mul_f32_e32 v119, 0xbfb8aa3b, v109
	v_exp_f32_e32 v118, v118
	v_exp_f32_e32 v119, v119
	s_movk_i32 s26, 0x1600
	v_mad_i64_i32 v[160:161], s[24:25], v154, s26, v[150:151]
	v_pk_mul_f32 v[122:123], v[122:123], v[124:125]
	v_lshlrev_b64 v[112:113], 1, v[156:157]
	v_lshl_add_u64 v[124:125], v[160:161], 0, v[112:113]
	v_cvt_pk_bf16_f32 v114, v120, v121
	v_cvt_pk_bf16_f32 v115, v122, v123
	global_store_dwordx4 v[124:125], v[114:117], off
	s_and_b64 vcc, exec, s[40:41]
	s_nop 0
	v_add_f32_e32 v114, 1.0, v118
	v_add_f32_e32 v115, 1.0, v119
	v_rcp_f32_e32 v114, v114
	v_rcp_f32_e32 v115, v115
	v_or_b32_e32 v116, 16, v154
	v_mad_i64_i32 v[116:117], s[24:25], v116, s26, v[150:151]
	v_pk_mul_f32 v[108:109], v[108:109], v[114:115]
	v_mul_f32_e32 v114, 0xbfb8aa3b, v110
	v_mul_f32_e32 v115, 0xbfb8aa3b, v111
	v_exp_f32_e32 v114, v114
	v_exp_f32_e32 v115, v115
	v_pk_mul_f32 v[104:105], v[104:105], v[108:109]
	v_add_f32_e32 v108, 1.0, v114
	v_add_f32_e32 v109, 1.0, v115
	v_mul_f32_e32 v114, 0xbfb8aa3b, v100
	v_mul_f32_e32 v115, 0xbfb8aa3b, v101
	v_rcp_f32_e32 v108, v108
	v_rcp_f32_e32 v109, v109
	v_exp_f32_e32 v114, v114
	v_exp_f32_e32 v115, v115
	v_pk_mul_f32 v[108:109], v[110:111], v[108:109]
	v_add_f32_e32 v110, 1.0, v114
	v_add_f32_e32 v111, 1.0, v115
	v_mul_f32_e32 v114, 0xbfb8aa3b, v102
	v_mul_f32_e32 v115, 0xbfb8aa3b, v103
	v_exp_f32_e32 v114, v114
	v_exp_f32_e32 v115, v115
	v_rcp_f32_e32 v110, v110
	v_rcp_f32_e32 v111, v111
	v_add_f32_e32 v114, 1.0, v114
	v_add_f32_e32 v115, 1.0, v115
	v_rcp_f32_e32 v114, v114
	v_rcp_f32_e32 v115, v115
	v_pk_mul_f32 v[100:101], v[100:101], v[110:111]
	v_pk_mul_f32 v[106:107], v[106:107], v[108:109]
	v_pk_mul_f32 v[100:101], v[96:97], v[100:101]
	v_pk_mul_f32 v[96:97], v[102:103], v[114:115]
	v_lshl_add_u64 v[108:109], v[116:117], 0, v[112:113]
	v_pk_mul_f32 v[102:103], v[98:99], v[96:97]
	v_cvt_pk_bf16_f32 v98, v100, v101
	v_mul_f32_e32 v100, 0xbfb8aa3b, v92
	v_mul_f32_e32 v101, 0xbfb8aa3b, v93
	v_exp_f32_e32 v100, v100
	v_exp_f32_e32 v101, v101
	v_cvt_pk_bf16_f32 v96, v104, v105
	v_cvt_pk_bf16_f32 v97, v106, v107
	v_cvt_pk_bf16_f32 v99, v102, v103
	global_store_dwordx4 v[108:109], v[96:99], off
	s_nop 1
	v_add_f32_e32 v96, 1.0, v100
	v_add_f32_e32 v97, 1.0, v101
	v_rcp_f32_e32 v96, v96
	v_rcp_f32_e32 v97, v97
	v_or_b32_e32 v98, 32, v154
	v_mad_i64_i32 v[98:99], s[24:25], v98, s26, v[150:151]
	v_pk_mul_f32 v[92:93], v[92:93], v[96:97]
	v_mul_f32_e32 v96, 0xbfb8aa3b, v94
	v_mul_f32_e32 v97, 0xbfb8aa3b, v95
	v_exp_f32_e32 v96, v96
	v_exp_f32_e32 v97, v97
	v_pk_mul_f32 v[88:89], v[88:89], v[92:93]
	v_add_f32_e32 v92, 1.0, v96
	v_add_f32_e32 v93, 1.0, v97
	v_mul_f32_e32 v96, 0xbfb8aa3b, v84
	v_mul_f32_e32 v97, 0xbfb8aa3b, v85
	v_rcp_f32_e32 v92, v92
	v_rcp_f32_e32 v93, v93
	v_exp_f32_e32 v96, v96
	v_exp_f32_e32 v97, v97
	v_pk_mul_f32 v[92:93], v[94:95], v[92:93]
	v_add_f32_e32 v94, 1.0, v96
	v_add_f32_e32 v95, 1.0, v97
	v_mul_f32_e32 v96, 0xbfb8aa3b, v86
	v_mul_f32_e32 v97, 0xbfb8aa3b, v87
	v_exp_f32_e32 v96, v96
	v_exp_f32_e32 v97, v97
	v_rcp_f32_e32 v94, v94
	v_rcp_f32_e32 v95, v95
	v_add_f32_e32 v96, 1.0, v96
	v_add_f32_e32 v97, 1.0, v97
	v_rcp_f32_e32 v96, v96
	v_rcp_f32_e32 v97, v97
	v_pk_mul_f32 v[84:85], v[84:85], v[94:95]
	v_pk_mul_f32 v[90:91], v[90:91], v[92:93]
	v_pk_mul_f32 v[84:85], v[80:81], v[84:85]
	v_pk_mul_f32 v[80:81], v[86:87], v[96:97]
	v_lshl_add_u64 v[92:93], v[98:99], 0, v[112:113]
	v_pk_mul_f32 v[86:87], v[82:83], v[80:81]
	v_cvt_pk_bf16_f32 v82, v84, v85
	v_mul_f32_e32 v84, 0xbfb8aa3b, v76
	v_mul_f32_e32 v85, 0xbfb8aa3b, v77
	v_exp_f32_e32 v84, v84
	v_exp_f32_e32 v85, v85
	v_cvt_pk_bf16_f32 v80, v88, v89
	v_cvt_pk_bf16_f32 v81, v90, v91
	v_cvt_pk_bf16_f32 v83, v86, v87
	global_store_dwordx4 v[92:93], v[80:83], off
	s_nop 1
	v_add_f32_e32 v80, 1.0, v84
	v_add_f32_e32 v81, 1.0, v85
	v_rcp_f32_e32 v80, v80
	v_rcp_f32_e32 v81, v81
	v_or_b32_e32 v82, 48, v154
	v_mad_i64_i32 v[82:83], s[24:25], v82, s26, v[150:151]
	v_pk_mul_f32 v[76:77], v[76:77], v[80:81]
	v_mul_f32_e32 v80, 0xbfb8aa3b, v78
	v_mul_f32_e32 v81, 0xbfb8aa3b, v79
	v_exp_f32_e32 v80, v80
	v_exp_f32_e32 v81, v81
	v_pk_mul_f32 v[72:73], v[72:73], v[76:77]
	v_add_f32_e32 v76, 1.0, v80
	v_add_f32_e32 v77, 1.0, v81
	v_mul_f32_e32 v80, 0xbfb8aa3b, v68
	v_mul_f32_e32 v81, 0xbfb8aa3b, v69
	v_rcp_f32_e32 v76, v76
	v_rcp_f32_e32 v77, v77
	v_exp_f32_e32 v80, v80
	v_exp_f32_e32 v81, v81
	v_pk_mul_f32 v[76:77], v[78:79], v[76:77]
	v_add_f32_e32 v78, 1.0, v80
	v_add_f32_e32 v79, 1.0, v81
	v_mul_f32_e32 v80, 0xbfb8aa3b, v70
	v_mul_f32_e32 v81, 0xbfb8aa3b, v71
	v_exp_f32_e32 v80, v80
	v_exp_f32_e32 v81, v81
	v_rcp_f32_e32 v78, v78
	v_rcp_f32_e32 v79, v79
	v_add_f32_e32 v80, 1.0, v80
	v_add_f32_e32 v81, 1.0, v81
	v_rcp_f32_e32 v80, v80
	v_rcp_f32_e32 v81, v81
	v_pk_mul_f32 v[68:69], v[68:69], v[78:79]
	v_pk_mul_f32 v[74:75], v[74:75], v[76:77]
	v_pk_mul_f32 v[68:69], v[64:65], v[68:69]
	v_pk_mul_f32 v[64:65], v[70:71], v[80:81]
	v_lshl_add_u64 v[76:77], v[82:83], 0, v[112:113]
	v_pk_mul_f32 v[70:71], v[66:67], v[64:65]
	v_cvt_pk_bf16_f32 v66, v68, v69
	v_mul_f32_e32 v68, 0xbfb8aa3b, v60
	v_mul_f32_e32 v69, 0xbfb8aa3b, v61
	v_exp_f32_e32 v68, v68
	v_exp_f32_e32 v69, v69
	v_cvt_pk_bf16_f32 v64, v72, v73
	v_cvt_pk_bf16_f32 v65, v74, v75
	v_cvt_pk_bf16_f32 v67, v70, v71
	global_store_dwordx4 v[76:77], v[64:67], off
	s_nop 1
	v_add_f32_e32 v64, 1.0, v68
	v_add_f32_e32 v65, 1.0, v69
	v_rcp_f32_e32 v64, v64
	v_rcp_f32_e32 v65, v65
	v_add_u32_e32 v66, 0x80, v154
	v_mad_i64_i32 v[66:67], s[24:25], v66, s26, v[150:151]
	v_pk_mul_f32 v[60:61], v[60:61], v[64:65]
	v_mul_f32_e32 v64, 0xbfb8aa3b, v62
	v_mul_f32_e32 v65, 0xbfb8aa3b, v63
	v_exp_f32_e32 v64, v64
	v_exp_f32_e32 v65, v65
	v_pk_mul_f32 v[56:57], v[56:57], v[60:61]
	v_add_f32_e32 v60, 1.0, v64
	v_add_f32_e32 v61, 1.0, v65
	v_mul_f32_e32 v64, 0xbfb8aa3b, v52
	v_mul_f32_e32 v65, 0xbfb8aa3b, v53
	v_rcp_f32_e32 v60, v60
	v_rcp_f32_e32 v61, v61
	v_exp_f32_e32 v64, v64
	v_exp_f32_e32 v65, v65
	v_pk_mul_f32 v[60:61], v[62:63], v[60:61]
	v_add_f32_e32 v62, 1.0, v64
	v_add_f32_e32 v63, 1.0, v65
	v_mul_f32_e32 v64, 0xbfb8aa3b, v54
	v_mul_f32_e32 v65, 0xbfb8aa3b, v55
	v_exp_f32_e32 v64, v64
	v_exp_f32_e32 v65, v65
	v_rcp_f32_e32 v62, v62
	v_rcp_f32_e32 v63, v63
	v_add_f32_e32 v64, 1.0, v64
	v_add_f32_e32 v65, 1.0, v65
	v_rcp_f32_e32 v64, v64
	v_rcp_f32_e32 v65, v65
	v_pk_mul_f32 v[52:53], v[52:53], v[62:63]
	v_pk_mul_f32 v[58:59], v[58:59], v[60:61]
	v_pk_mul_f32 v[52:53], v[48:49], v[52:53]
	v_pk_mul_f32 v[48:49], v[54:55], v[64:65]
	v_lshl_add_u64 v[60:61], v[66:67], 0, v[112:113]
	v_pk_mul_f32 v[54:55], v[50:51], v[48:49]
	v_cvt_pk_bf16_f32 v50, v52, v53
	v_mul_f32_e32 v52, 0xbfb8aa3b, v44
	v_mul_f32_e32 v53, 0xbfb8aa3b, v45
	v_exp_f32_e32 v52, v52
	v_exp_f32_e32 v53, v53
	v_cvt_pk_bf16_f32 v48, v56, v57
	v_cvt_pk_bf16_f32 v49, v58, v59
	v_cvt_pk_bf16_f32 v51, v54, v55
	global_store_dwordx4 v[60:61], v[48:51], off
	s_nop 1
	v_add_f32_e32 v48, 1.0, v52
	v_add_f32_e32 v49, 1.0, v53
	v_rcp_f32_e32 v48, v48
	v_rcp_f32_e32 v49, v49
	v_add_u32_e32 v50, 0x90, v154
	v_mad_i64_i32 v[50:51], s[24:25], v50, s26, v[150:151]
	v_pk_mul_f32 v[44:45], v[44:45], v[48:49]
	v_mul_f32_e32 v48, 0xbfb8aa3b, v46
	v_mul_f32_e32 v49, 0xbfb8aa3b, v47
	v_exp_f32_e32 v48, v48
	v_exp_f32_e32 v49, v49
	v_pk_mul_f32 v[40:41], v[40:41], v[44:45]
	v_add_f32_e32 v44, 1.0, v48
	v_add_f32_e32 v45, 1.0, v49
	v_mul_f32_e32 v48, 0xbfb8aa3b, v36
	v_mul_f32_e32 v49, 0xbfb8aa3b, v37
	v_rcp_f32_e32 v44, v44
	v_rcp_f32_e32 v45, v45
	v_exp_f32_e32 v48, v48
	v_exp_f32_e32 v49, v49
	v_pk_mul_f32 v[44:45], v[46:47], v[44:45]
	v_add_f32_e32 v46, 1.0, v48
	v_add_f32_e32 v47, 1.0, v49
	v_mul_f32_e32 v48, 0xbfb8aa3b, v38
	v_mul_f32_e32 v49, 0xbfb8aa3b, v39
	v_exp_f32_e32 v48, v48
	v_exp_f32_e32 v49, v49
	v_rcp_f32_e32 v46, v46
	v_rcp_f32_e32 v47, v47
	v_add_f32_e32 v48, 1.0, v48
	v_add_f32_e32 v49, 1.0, v49
	v_rcp_f32_e32 v48, v48
	v_rcp_f32_e32 v49, v49
	v_pk_mul_f32 v[36:37], v[36:37], v[46:47]
	v_pk_mul_f32 v[42:43], v[42:43], v[44:45]
	v_pk_mul_f32 v[36:37], v[32:33], v[36:37]
	v_pk_mul_f32 v[32:33], v[38:39], v[48:49]
	v_lshl_add_u64 v[44:45], v[50:51], 0, v[112:113]
	v_pk_mul_f32 v[38:39], v[34:35], v[32:33]
	v_cvt_pk_bf16_f32 v34, v36, v37
	v_mul_f32_e32 v36, 0xbfb8aa3b, v28
	v_mul_f32_e32 v37, 0xbfb8aa3b, v29
	v_exp_f32_e32 v36, v36
	v_exp_f32_e32 v37, v37
	v_cvt_pk_bf16_f32 v32, v40, v41
	v_cvt_pk_bf16_f32 v33, v42, v43
	v_cvt_pk_bf16_f32 v35, v38, v39
	global_store_dwordx4 v[44:45], v[32:35], off
	s_nop 1
	v_add_f32_e32 v32, 1.0, v36
	v_add_f32_e32 v33, 1.0, v37
	v_rcp_f32_e32 v32, v32
	v_rcp_f32_e32 v33, v33
	v_add_u32_e32 v34, 0xa0, v154
	v_mad_i64_i32 v[34:35], s[24:25], v34, s26, v[150:151]
	v_pk_mul_f32 v[28:29], v[28:29], v[32:33]
	v_mul_f32_e32 v32, 0xbfb8aa3b, v30
	v_mul_f32_e32 v33, 0xbfb8aa3b, v31
	v_exp_f32_e32 v32, v32
	v_exp_f32_e32 v33, v33
	v_pk_mul_f32 v[24:25], v[24:25], v[28:29]
	v_add_f32_e32 v28, 1.0, v32
	v_add_f32_e32 v29, 1.0, v33
	v_mul_f32_e32 v32, 0xbfb8aa3b, v20
	v_mul_f32_e32 v33, 0xbfb8aa3b, v21
	v_rcp_f32_e32 v28, v28
	v_rcp_f32_e32 v29, v29
	v_exp_f32_e32 v32, v32
	v_exp_f32_e32 v33, v33
	v_pk_mul_f32 v[28:29], v[30:31], v[28:29]
	v_add_f32_e32 v30, 1.0, v32
	v_add_f32_e32 v31, 1.0, v33
	v_mul_f32_e32 v32, 0xbfb8aa3b, v22
	v_mul_f32_e32 v33, 0xbfb8aa3b, v23
	v_exp_f32_e32 v32, v32
	v_exp_f32_e32 v33, v33
	v_rcp_f32_e32 v30, v30
	v_rcp_f32_e32 v31, v31
	v_add_f32_e32 v32, 1.0, v32
	v_add_f32_e32 v33, 1.0, v33
	v_rcp_f32_e32 v32, v32
	v_rcp_f32_e32 v33, v33
	v_pk_mul_f32 v[20:21], v[20:21], v[30:31]
	v_pk_mul_f32 v[26:27], v[26:27], v[28:29]
	v_pk_mul_f32 v[20:21], v[16:17], v[20:21]
	v_pk_mul_f32 v[16:17], v[22:23], v[32:33]
	v_lshl_add_u64 v[28:29], v[34:35], 0, v[112:113]
	v_pk_mul_f32 v[22:23], v[18:19], v[16:17]
	v_cvt_pk_bf16_f32 v18, v20, v21
	v_mul_f32_e32 v20, 0xbfb8aa3b, v12
	v_mul_f32_e32 v21, 0xbfb8aa3b, v13
	v_exp_f32_e32 v20, v20
	v_exp_f32_e32 v21, v21
	v_cvt_pk_bf16_f32 v16, v24, v25
	v_cvt_pk_bf16_f32 v17, v26, v27
	v_cvt_pk_bf16_f32 v19, v22, v23
	global_store_dwordx4 v[28:29], v[16:19], off
	s_nop 1
	v_add_f32_e32 v16, 1.0, v20
	v_add_f32_e32 v17, 1.0, v21
	v_rcp_f32_e32 v16, v16
	v_rcp_f32_e32 v17, v17
	v_add_u32_e32 v18, 0xb0, v154
	v_mad_i64_i32 v[18:19], s[24:25], v18, s26, v[150:151]
	v_pk_mul_f32 v[12:13], v[12:13], v[16:17]
	v_mul_f32_e32 v16, 0xbfb8aa3b, v14
	v_mul_f32_e32 v17, 0xbfb8aa3b, v15
	v_exp_f32_e32 v16, v16
	v_exp_f32_e32 v17, v17
	v_pk_mul_f32 v[8:9], v[8:9], v[12:13]
	s_mov_b64 s[24:25], -1
	v_add_f32_e32 v12, 1.0, v16
	v_add_f32_e32 v13, 1.0, v17
	v_mul_f32_e32 v16, 0xbfb8aa3b, v4
	v_mul_f32_e32 v17, 0xbfb8aa3b, v5
	v_rcp_f32_e32 v12, v12
	v_rcp_f32_e32 v13, v13
	v_exp_f32_e32 v16, v16
	v_exp_f32_e32 v17, v17
	v_pk_mul_f32 v[12:13], v[14:15], v[12:13]
	v_add_f32_e32 v14, 1.0, v16
	v_add_f32_e32 v15, 1.0, v17
	v_mul_f32_e32 v16, 0xbfb8aa3b, v6
	v_mul_f32_e32 v17, 0xbfb8aa3b, v7
	v_exp_f32_e32 v16, v16
	v_exp_f32_e32 v17, v17
	v_rcp_f32_e32 v14, v14
	v_rcp_f32_e32 v15, v15
	v_add_f32_e32 v16, 1.0, v16
	v_add_f32_e32 v17, 1.0, v17
	v_rcp_f32_e32 v16, v16
	v_rcp_f32_e32 v17, v17
	v_pk_mul_f32 v[4:5], v[4:5], v[14:15]
	v_pk_mul_f32 v[10:11], v[10:11], v[12:13]
	v_pk_mul_f32 v[4:5], v[0:1], v[4:5]
	v_pk_mul_f32 v[0:1], v[6:7], v[16:17]
	v_lshl_add_u64 v[12:13], v[18:19], 0, v[112:113]
	v_pk_mul_f32 v[6:7], v[2:3], v[0:1]
	v_cvt_pk_bf16_f32 v0, v8, v9
	v_cvt_pk_bf16_f32 v1, v10, v11
	v_cvt_pk_bf16_f32 v2, v4, v5
	v_cvt_pk_bf16_f32 v3, v6, v7
	global_store_dwordx4 v[12:13], v[0:3], off
	s_cbranch_vccnz .LBB0_94
	s_andn2_b64 vcc, exec, s[12:13]
	s_cbranch_vccnz .LBB0_93
	s_barrier
	s_branch .LBB0_93

.LBB0_124:
	s_add_i32 m0, s38, 0x18000
	v_lshl_add_u64 v[0:1], v[0:1], 0, s[98:99]
	s_waitcnt vmcnt(2)
	s_barrier
	global_load_lds_dwordx4 v[0:1], off
	v_lshl_add_u64 v[0:1], v[2:3], 0, s[98:99]
	s_add_i32 m0, s38, 0x1a000
	s_add_i32 s44, s38, 0x8000
	global_load_lds_dwordx4 v[0:1], off
	v_lshl_add_u64 v[0:1], v[8:9], 0, s[98:99]
	s_mov_b32 m0, s44
	s_add_i32 s45, s38, 0xa000
	global_load_lds_dwordx4 v[0:1], off
	v_lshl_add_u64 v[0:1], v[10:11], 0, s[98:99]
	s_mov_b32 m0, s45
	v_readlane_b32 s16, v255, 23
	global_load_lds_dwordx4 v[0:1], off
	s_add_i32 m0, s38, 0x1c000
	v_lshl_add_u64 v[0:1], v[4:5], 0, s[98:99]
	global_load_lds_dwordx4 v[0:1], off
	v_lshl_add_u64 v[0:1], v[6:7], 0, s[98:99]
	s_add_i32 m0, s38, 0x1e000
	v_readlane_b32 s17, v255, 24
	global_load_lds_dwordx4 v[0:1], off
	v_lshrrev_b32_e32 v1, 1, v12
	v_and_b32_e32 v1, 24, v1
	v_and_b32_e32 v0, 15, v12
	v_lshlrev_b32_e32 v2, 1, v1
	v_lshl_or_b32 v135, s14, 6, v0
	v_lshl_or_b32 v0, v0, 6, v2
	v_lshlrev_b32_e32 v2, 2, v12
	s_lshl_b32 s1, s1, 5
	s_lshr_b32 s15, s17, 26
	s_lshl_b32 s14, s14, 13
	v_and_b32_e32 v2, 32, v2
	s_and_b32 s1, s1, 0x60
	s_add_i32 s15, s16, s15
	v_bitop3_b32 v3, v0, s14, v2 bitop3:0xde
	s_lshl_b32 s14, s1, 7
	s_ashr_i32 s46, s15, 6
	v_bitop3_b32 v137, v0, s14, v2 bitop3:0xde
	v_add_u32_e32 v0, v18, v16
	s_cmp_gt_i32 s16, 63
	v_or_b32_e32 v156, s1, v1
	v_add_lshl_u32 v0, v0, v17, 1
	v_mov_b32_e32 v1, v129
	s_waitcnt vmcnt(6)
	s_cselect_b64 s[14:15], -1, 0
	s_add_i32 s47, s46, -2
	v_lshl_add_u64 v[146:147], s[2:3], 0, v[0:1]
	v_add_u32_e32 v0, v15, v13
	s_cmpk_lt_u32 s0, 0x100
	v_add_lshl_u32 v0, v0, v14, 1
	s_cselect_b64 s[16:17], -1, 0
	s_waitcnt lgkmcnt(0)
	s_ashr_i32 s48, s34, 31
	v_lshl_add_u64 v[148:149], s[2:3], 0, v[0:1]
	s_mov_b32 s49, 0
	v_add_u32_e32 v157, 16, v3
	v_readlane_b32 s52, v254, 48
	v_readlane_b32 s53, v254, 54
	s_barrier
	s_mov_b32 s101, 0
	s_branch .LBB0_127

.LBB0_139:
	s_cmp_eq_u32 s26, 0
	s_cselect_b32 s100, s101, 0
	s_add_i32 s54, s26, 2
	s_add_u32 s55, s0, 0x80
	s_addc_u32 s27, s1, 0
	s_add_i32 s58, 16, 0x10000
	s_cmp_eq_u32 s47, s26
	s_cselect_b32 s27, s21, s27
	s_cselect_b32 s26, s20, s55
	v_add_u32_e32 v154, s58, v137
	s_cselect_b32 s57, s25, s29
	s_cselect_b32 s56, s24, s28
	s_add_i32 s55, 16, 0x14000
	ds_read_b128 v[150:153], v154
	ds_read_b128 v[158:161], v154 offset:1024
	ds_read_b128 v[162:165], v154 offset:2048
	ds_read_b128 v[166:169], v154 offset:3072
	v_add_u32_e32 v154, s55, v137
	ds_read_b128 v[170:173], v154
	ds_read_b128 v[174:177], v154 offset:1024
	ds_read_b128 v[178:181], v154 offset:2048
	ds_read_b128 v[182:185], v154 offset:3072
	v_lshl_add_u64 v[154:155], s[0:1], 0, v[146:147]
	s_add_i32 m0, s38, 0xc000
	ds_read_b128 v[186:189], v157
	ds_read_b128 v[190:193], v157 offset:1024
	ds_read_b128 v[194:197], v157 offset:2048
	ds_read_b128 v[220:223], v157 offset:3072
	ds_read_b128 v[224:227], v157 offset:4096
	ds_read_b128 v[228:231], v157 offset:5120
	ds_read_b128 v[232:235], v157 offset:6144
	ds_read_b128 v[236:239], v157 offset:7168
	global_load_lds_dwordx4 v[154:155], off
	v_lshl_add_u64 v[154:155], s[0:1], 0, v[148:149]
	s_add_i32 m0, s38, 0xe000
	s_nop 0
	global_load_lds_dwordx4 v[154:155], off
	s_cmp_eq_u32 s100, 0
	s_cbranch_scc1 .Lgw8_2_0
	s_cmp_eq_u32 s100, 8
	s_cbranch_scc1 .Lgw16_2_0
	s_waitcnt vmcnt(24)
	s_branch .Lgwd_2_0

.Lgwd_2_0:
	s_waitcnt lgkmcnt(0)
	s_barrier
	s_setprio 1
	s_waitcnt lgkmcnt(0)
	v_mfma_f32_16x16x32_bf16 v[120:123], v[150:153], v[186:189], v[120:123]
	v_mfma_f32_16x16x32_bf16 v[124:127], v[162:165], v[186:189], v[124:127]
	v_mfma_f32_16x16x32_bf16 v[108:111], v[150:153], v[194:197], v[108:111]
	v_mfma_f32_16x16x32_bf16 v[104:107], v[162:165], v[194:197], v[104:107]
	v_mfma_f32_16x16x32_bf16 v[92:95], v[150:153], v[224:227], v[92:95]
	v_mfma_f32_16x16x32_bf16 v[88:91], v[162:165], v[224:227], v[88:91]
	v_mfma_f32_16x16x32_bf16 v[76:79], v[150:153], v[232:235], v[76:79]
	v_mfma_f32_16x16x32_bf16 v[72:75], v[162:165], v[232:235], v[72:75]
	v_mfma_f32_16x16x32_bf16 v[120:123], v[158:161], v[190:193], v[120:123]
	v_mfma_f32_16x16x32_bf16 v[124:127], v[166:169], v[190:193], v[124:127]
	v_mfma_f32_16x16x32_bf16 v[108:111], v[158:161], v[220:223], v[108:111]
	v_mfma_f32_16x16x32_bf16 v[104:107], v[166:169], v[220:223], v[104:107]
	v_mfma_f32_16x16x32_bf16 v[92:95], v[158:161], v[228:231], v[92:95]
	v_mfma_f32_16x16x32_bf16 v[88:91], v[166:169], v[228:231], v[88:91]
	v_mfma_f32_16x16x32_bf16 v[76:79], v[158:161], v[236:239], v[76:79]
	v_mfma_f32_16x16x32_bf16 v[72:75], v[166:169], v[236:239], v[72:75]
	s_setprio 0
	s_setprio 1
	v_mfma_f32_16x16x32_bf16 v[116:119], v[170:173], v[186:189], v[116:119]
	v_mfma_f32_16x16x32_bf16 v[112:115], v[178:181], v[186:189], v[112:115]
	v_mfma_f32_16x16x32_bf16 v[100:103], v[170:173], v[194:197], v[100:103]
	v_mfma_f32_16x16x32_bf16 v[96:99], v[178:181], v[194:197], v[96:99]
	v_mfma_f32_16x16x32_bf16 v[84:87], v[170:173], v[224:227], v[84:87]
	v_mfma_f32_16x16x32_bf16 v[80:83], v[178:181], v[224:227], v[80:83]
	v_mfma_f32_16x16x32_bf16 v[68:71], v[170:173], v[232:235], v[68:71]
	v_mfma_f32_16x16x32_bf16 v[64:67], v[178:181], v[232:235], v[64:67]
	v_mfma_f32_16x16x32_bf16 v[116:119], v[174:177], v[190:193], v[116:119]
	v_mfma_f32_16x16x32_bf16 v[112:115], v[182:185], v[190:193], v[112:115]
	v_mfma_f32_16x16x32_bf16 v[100:103], v[174:177], v[220:223], v[100:103]
	v_mfma_f32_16x16x32_bf16 v[96:99], v[182:185], v[220:223], v[96:99]
	v_mfma_f32_16x16x32_bf16 v[84:87], v[174:177], v[228:231], v[84:87]
	v_mfma_f32_16x16x32_bf16 v[80:83], v[182:185], v[228:231], v[80:83]
	v_mfma_f32_16x16x32_bf16 v[68:71], v[174:177], v[236:239], v[68:71]
	v_mfma_f32_16x16x32_bf16 v[64:67], v[182:185], v[236:239], v[64:67]
	s_setprio 0
	s_barrier
	s_add_i32 s58, s58, s35
	v_lshl_add_u64 v[154:155], s[56:57], 0, v[128:129]
	s_mov_b32 m0, s58
	ds_read_b128 v[186:189], v157 offset:16384
	ds_read_b128 v[190:193], v157 offset:17408
	ds_read_b128 v[194:197], v157 offset:18432
	ds_read_b128 v[220:223], v157 offset:19456
	ds_read_b128 v[224:227], v157 offset:20480
	ds_read_b128 v[228:231], v157 offset:21504
	ds_read_b128 v[232:235], v157 offset:22528
	ds_read_b128 v[236:239], v157 offset:23552
	global_load_lds_dwordx4 v[154:155], off
	s_add_i32 m0, s58, 0x2000
	v_lshl_add_u64 v[198:199], s[56:57], 0, v[140:141]
	s_add_u32 s56, s56, s2
	s_addc_u32 s57, s57, s3
	s_add_i32 s55, s55, s35
	global_load_lds_dwordx4 v[198:199], off
	v_lshl_add_u64 v[208:209], s[56:57], 0, v[128:129]
	s_mov_b32 m0, s55
	v_lshl_add_u64 v[244:245], s[56:57], 0, v[140:141]
	global_load_lds_dwordx4 v[208:209], off
	s_add_i32 m0, s55, 0x2000
	v_lshl_add_u64 v[246:247], s[26:27], 0, v[144:145]
	global_load_lds_dwordx4 v[244:245], off
	s_mov_b32 m0, s38
	v_lshl_add_u64 v[248:249], s[26:27], 0, v[142:143]
	global_load_lds_dwordx4 v[246:247], off
	s_mov_b32 m0, s39
	s_nop 0
	global_load_lds_dwordx4 v[248:249], off
	s_cmp_eq_u32 s100, 0
	s_cbranch_scc1 .Lgw8_2_1
	s_cmp_eq_u32 s100, 8
	s_cbranch_scc1 .Lgw16_2_1
	s_waitcnt vmcnt(24)
	s_branch .Lgwd_2_1

.Lgwd_2_1:
	s_waitcnt lgkmcnt(0)
	s_barrier
	s_setprio 1
	s_waitcnt lgkmcnt(0)
	v_mfma_f32_16x16x32_bf16 v[60:63], v[150:153], v[186:189], v[60:63]
	v_mfma_f32_16x16x32_bf16 v[56:59], v[162:165], v[186:189], v[56:59]
	v_mfma_f32_16x16x32_bf16 v[44:47], v[150:153], v[194:197], v[44:47]
	v_mfma_f32_16x16x32_bf16 v[40:43], v[162:165], v[194:197], v[40:43]
	v_mfma_f32_16x16x32_bf16 v[28:31], v[150:153], v[224:227], v[28:31]
	v_mfma_f32_16x16x32_bf16 v[24:27], v[162:165], v[224:227], v[24:27]
	v_mfma_f32_16x16x32_bf16 v[12:15], v[150:153], v[232:235], v[12:15]
	v_mfma_f32_16x16x32_bf16 v[8:11], v[162:165], v[232:235], v[8:11]
	v_mfma_f32_16x16x32_bf16 v[60:63], v[158:161], v[190:193], v[60:63]
	v_mfma_f32_16x16x32_bf16 v[56:59], v[166:169], v[190:193], v[56:59]
	v_mfma_f32_16x16x32_bf16 v[44:47], v[158:161], v[220:223], v[44:47]
	v_mfma_f32_16x16x32_bf16 v[40:43], v[166:169], v[220:223], v[40:43]
	v_mfma_f32_16x16x32_bf16 v[28:31], v[158:161], v[228:231], v[28:31]
	v_mfma_f32_16x16x32_bf16 v[24:27], v[166:169], v[228:231], v[24:27]
	v_mfma_f32_16x16x32_bf16 v[12:15], v[158:161], v[236:239], v[12:15]
	v_mfma_f32_16x16x32_bf16 v[8:11], v[166:169], v[236:239], v[8:11]
	s_setprio 0
	s_setprio 1
	v_mfma_f32_16x16x32_bf16 v[52:55], v[170:173], v[186:189], v[52:55]
	v_mfma_f32_16x16x32_bf16 v[48:51], v[178:181], v[186:189], v[48:51]
	v_mfma_f32_16x16x32_bf16 v[36:39], v[170:173], v[194:197], v[36:39]
	v_mfma_f32_16x16x32_bf16 v[32:35], v[178:181], v[194:197], v[32:35]
	v_mfma_f32_16x16x32_bf16 v[20:23], v[170:173], v[224:227], v[20:23]
	v_mfma_f32_16x16x32_bf16 v[16:19], v[178:181], v[224:227], v[16:19]
	v_mfma_f32_16x16x32_bf16 v[4:7], v[170:173], v[232:235], v[4:7]
	v_mfma_f32_16x16x32_bf16 v[0:3], v[178:181], v[232:235], v[0:3]
	v_mfma_f32_16x16x32_bf16 v[52:55], v[174:177], v[190:193], v[52:55]
	v_mfma_f32_16x16x32_bf16 v[48:51], v[182:185], v[190:193], v[48:51]
	v_mfma_f32_16x16x32_bf16 v[36:39], v[174:177], v[220:223], v[36:39]
	v_mfma_f32_16x16x32_bf16 v[32:35], v[182:185], v[220:223], v[32:35]
	v_mfma_f32_16x16x32_bf16 v[20:23], v[174:177], v[228:231], v[20:23]
	v_mfma_f32_16x16x32_bf16 v[16:19], v[182:185], v[228:231], v[16:19]
	v_mfma_f32_16x16x32_bf16 v[4:7], v[174:177], v[236:239], v[4:7]
	v_mfma_f32_16x16x32_bf16 v[0:3], v[182:185], v[236:239], v[0:3]
	s_setprio 0
	s_barrier
	s_add_i32 s55, 16, 0x18000
	s_add_i32 s56, 16, 0x1c000
	v_add_u32_e32 v166, s55, v137
	v_add_u32_e32 v182, s56, v137
	ds_read_b128 v[150:153], v166
	ds_read_b128 v[158:161], v166 offset:1024
	ds_read_b128 v[162:165], v166 offset:2048
	ds_read_b128 v[166:169], v166 offset:3072
	ds_read_b128 v[170:173], v182
	ds_read_b128 v[174:177], v182 offset:1024
	ds_read_b128 v[178:181], v182 offset:2048
	ds_read_b128 v[182:185], v182 offset:3072
	s_add_u32 s26, s26, s2
	s_addc_u32 s27, s27, s3
	s_mov_b32 m0, s42
	v_lshl_add_u64 v[250:251], s[26:27], 0, v[144:145]
	ds_read_b128 v[186:189], v157 offset:32768
	ds_read_b128 v[190:193], v157 offset:33792
	ds_read_b128 v[194:197], v157 offset:34816
	ds_read_b128 v[220:223], v157 offset:35840
	ds_read_b128 v[224:227], v157 offset:36864
	ds_read_b128 v[228:231], v157 offset:37888
	ds_read_b128 v[232:235], v157 offset:38912
	ds_read_b128 v[236:239], v157 offset:39936
	global_load_lds_dwordx4 v[250:251], off
	v_lshl_add_u64 v[250:251], s[26:27], 0, v[142:143]
	s_mov_b32 m0, s43
	s_nop 0
	global_load_lds_dwordx4 v[250:251], off
	s_waitcnt vmcnt(8)
	s_waitcnt lgkmcnt(0)
	s_barrier
	s_setprio 1
	s_waitcnt lgkmcnt(0)
	v_mfma_f32_16x16x32_bf16 v[120:123], v[150:153], v[186:189], v[120:123]
	v_mfma_f32_16x16x32_bf16 v[124:127], v[162:165], v[186:189], v[124:127]
	v_mfma_f32_16x16x32_bf16 v[108:111], v[150:153], v[194:197], v[108:111]
	v_mfma_f32_16x16x32_bf16 v[104:107], v[162:165], v[194:197], v[104:107]
	v_mfma_f32_16x16x32_bf16 v[92:95], v[150:153], v[224:227], v[92:95]
	v_mfma_f32_16x16x32_bf16 v[88:91], v[162:165], v[224:227], v[88:91]
	v_mfma_f32_16x16x32_bf16 v[76:79], v[150:153], v[232:235], v[76:79]
	v_mfma_f32_16x16x32_bf16 v[72:75], v[162:165], v[232:235], v[72:75]
	v_mfma_f32_16x16x32_bf16 v[120:123], v[158:161], v[190:193], v[120:123]
	v_mfma_f32_16x16x32_bf16 v[124:127], v[166:169], v[190:193], v[124:127]
	v_mfma_f32_16x16x32_bf16 v[108:111], v[158:161], v[220:223], v[108:111]
	v_mfma_f32_16x16x32_bf16 v[104:107], v[166:169], v[220:223], v[104:107]
	v_mfma_f32_16x16x32_bf16 v[92:95], v[158:161], v[228:231], v[92:95]
	v_mfma_f32_16x16x32_bf16 v[88:91], v[166:169], v[228:231], v[88:91]
	v_mfma_f32_16x16x32_bf16 v[76:79], v[158:161], v[236:239], v[76:79]
	v_mfma_f32_16x16x32_bf16 v[72:75], v[166:169], v[236:239], v[72:75]
	s_setprio 0
	s_setprio 1
	v_mfma_f32_16x16x32_bf16 v[116:119], v[170:173], v[186:189], v[116:119]
	v_mfma_f32_16x16x32_bf16 v[112:115], v[178:181], v[186:189], v[112:115]
	v_mfma_f32_16x16x32_bf16 v[100:103], v[170:173], v[194:197], v[100:103]
	v_mfma_f32_16x16x32_bf16 v[96:99], v[178:181], v[194:197], v[96:99]
	v_mfma_f32_16x16x32_bf16 v[84:87], v[170:173], v[224:227], v[84:87]
	v_mfma_f32_16x16x32_bf16 v[80:83], v[178:181], v[224:227], v[80:83]
	v_mfma_f32_16x16x32_bf16 v[68:71], v[170:173], v[232:235], v[68:71]
	v_mfma_f32_16x16x32_bf16 v[64:67], v[178:181], v[232:235], v[64:67]
	v_mfma_f32_16x16x32_bf16 v[116:119], v[174:177], v[190:193], v[116:119]
	v_mfma_f32_16x16x32_bf16 v[112:115], v[182:185], v[190:193], v[112:115]
	v_mfma_f32_16x16x32_bf16 v[100:103], v[174:177], v[220:223], v[100:103]
	v_mfma_f32_16x16x32_bf16 v[96:99], v[182:185], v[220:223], v[96:99]
	v_mfma_f32_16x16x32_bf16 v[84:87], v[174:177], v[228:231], v[84:87]
	v_mfma_f32_16x16x32_bf16 v[80:83], v[182:185], v[228:231], v[80:83]
	v_mfma_f32_16x16x32_bf16 v[68:71], v[174:177], v[236:239], v[68:71]
	v_mfma_f32_16x16x32_bf16 v[64:67], v[182:185], v[236:239], v[64:67]
	s_setprio 0
	s_barrier
	s_add_i32 s26, s55, s35
	v_lshl_add_u64 v[154:155], v[154:155], 0, s[98:99]
	s_mov_b32 m0, s26
	ds_read_b128 v[186:189], v157 offset:49152
	ds_read_b128 v[190:193], v157 offset:50176
	ds_read_b128 v[194:197], v157 offset:51200
	ds_read_b128 v[220:223], v157 offset:52224
	ds_read_b128 v[224:227], v157 offset:53248
	ds_read_b128 v[228:231], v157 offset:54272
	ds_read_b128 v[232:235], v157 offset:55296
	ds_read_b128 v[236:239], v157 offset:56320
	global_load_lds_dwordx4 v[154:155], off
	v_lshl_add_u64 v[154:155], v[198:199], 0, s[98:99]
	s_add_i32 m0, s26, 0x2000
	s_add_i32 s26, s56, s35
	global_load_lds_dwordx4 v[154:155], off
	v_lshl_add_u64 v[154:155], v[208:209], 0, s[98:99]
	s_mov_b32 m0, s26
	s_nop 0
	global_load_lds_dwordx4 v[154:155], off
	v_lshl_add_u64 v[154:155], v[244:245], 0, s[98:99]
	s_add_i32 m0, s26, 0x2000
	s_nop 0
	global_load_lds_dwordx4 v[154:155], off
	v_lshl_add_u64 v[154:155], v[246:247], 0, s[98:99]
	s_mov_b32 m0, s44
	s_nop 0
	global_load_lds_dwordx4 v[154:155], off
	v_lshl_add_u64 v[154:155], v[248:249], 0, s[98:99]
	s_mov_b32 m0, s45
	s_nop 0
	global_load_lds_dwordx4 v[154:155], off
	s_waitcnt vmcnt(8)
	s_waitcnt lgkmcnt(0)
	s_barrier
	s_setprio 1
	s_waitcnt lgkmcnt(0)
	v_mfma_f32_16x16x32_bf16 v[60:63], v[150:153], v[186:189], v[60:63]
	v_mfma_f32_16x16x32_bf16 v[56:59], v[162:165], v[186:189], v[56:59]
	v_mfma_f32_16x16x32_bf16 v[44:47], v[150:153], v[194:197], v[44:47]
	v_mfma_f32_16x16x32_bf16 v[40:43], v[162:165], v[194:197], v[40:43]
	v_mfma_f32_16x16x32_bf16 v[28:31], v[150:153], v[224:227], v[28:31]
	v_mfma_f32_16x16x32_bf16 v[24:27], v[162:165], v[224:227], v[24:27]
	v_mfma_f32_16x16x32_bf16 v[12:15], v[150:153], v[232:235], v[12:15]
	v_mfma_f32_16x16x32_bf16 v[8:11], v[162:165], v[232:235], v[8:11]
	v_mfma_f32_16x16x32_bf16 v[60:63], v[158:161], v[190:193], v[60:63]
	v_mfma_f32_16x16x32_bf16 v[56:59], v[166:169], v[190:193], v[56:59]
	v_mfma_f32_16x16x32_bf16 v[44:47], v[158:161], v[220:223], v[44:47]
	v_mfma_f32_16x16x32_bf16 v[40:43], v[166:169], v[220:223], v[40:43]
	v_mfma_f32_16x16x32_bf16 v[28:31], v[158:161], v[228:231], v[28:31]
	v_mfma_f32_16x16x32_bf16 v[24:27], v[166:169], v[228:231], v[24:27]
	v_mfma_f32_16x16x32_bf16 v[12:15], v[158:161], v[236:239], v[12:15]
	v_mfma_f32_16x16x32_bf16 v[8:11], v[166:169], v[236:239], v[8:11]
	s_setprio 0
	s_setprio 1
	v_mfma_f32_16x16x32_bf16 v[52:55], v[170:173], v[186:189], v[52:55]
	v_mfma_f32_16x16x32_bf16 v[48:51], v[178:181], v[186:189], v[48:51]
	v_mfma_f32_16x16x32_bf16 v[36:39], v[170:173], v[194:197], v[36:39]
	v_mfma_f32_16x16x32_bf16 v[32:35], v[178:181], v[194:197], v[32:35]
	v_mfma_f32_16x16x32_bf16 v[20:23], v[170:173], v[224:227], v[20:23]
	v_mfma_f32_16x16x32_bf16 v[16:19], v[178:181], v[224:227], v[16:19]
	v_mfma_f32_16x16x32_bf16 v[4:7], v[170:173], v[232:235], v[4:7]
	v_mfma_f32_16x16x32_bf16 v[0:3], v[178:181], v[232:235], v[0:3]
	v_mfma_f32_16x16x32_bf16 v[52:55], v[174:177], v[190:193], v[52:55]
	v_mfma_f32_16x16x32_bf16 v[48:51], v[182:185], v[190:193], v[48:51]
	v_mfma_f32_16x16x32_bf16 v[36:39], v[174:177], v[220:223], v[36:39]
	v_mfma_f32_16x16x32_bf16 v[32:35], v[182:185], v[220:223], v[32:35]
	v_mfma_f32_16x16x32_bf16 v[20:23], v[174:177], v[228:231], v[20:23]
	v_mfma_f32_16x16x32_bf16 v[16:19], v[182:185], v[228:231], v[16:19]
	v_mfma_f32_16x16x32_bf16 v[4:7], v[174:177], v[236:239], v[4:7]
	v_mfma_f32_16x16x32_bf16 v[0:3], v[182:185], v[236:239], v[0:3]
	s_setprio 0
	s_barrier
	s_add_u32 s0, s0, 0x100
	s_addc_u32 s1, s1, 0
	s_add_u32 s28, s28, 0x100
	s_addc_u32 s29, s29, 0
	s_cmp_ge_i32 s54, s46
	s_mov_b32 s26, s54
	s_cbranch_scc0 .LBB0_139
	v_readlane_b32 s58, v255, 20
	v_readlane_b32 s59, v255, 21

.LBB0_143:
	s_mov_b32 s101, 16
	v_lshl_add_u32 v152, s53, 8, v135
	v_ashrrev_i32_e32 v153, 31, v152
	v_lshl_or_b32 v150, s52, 8, v156
	v_lshlrev_b64 v[154:155], 11, v[152:153]
	v_ashrrev_i32_e32 v151, 31, v150
	v_lshl_add_u64 v[154:155], s[4:5], 0, v[154:155]
	s_movk_i32 s0, 0x400
	v_lshl_add_u64 v[154:155], v[150:151], 1, v[154:155]
	v_cmp_gt_i32_e32 vcc, s0, v150
	s_and_saveexec_b64 s[0:1], vcc
	s_cbranch_execz .LBB0_145
	v_cvt_pk_bf16_f32 v120, v120, v121
	v_cvt_pk_bf16_f32 v121, v122, v123
	v_cvt_pk_bf16_f32 v122, v124, v125
	v_cvt_pk_bf16_f32 v123, v126, v127
	global_store_dwordx4 v[154:155], v[120:123], off

.LBB0_324:
	s_add_i32 m0, s37, 0x18000
	v_lshl_add_u64 v[8:9], v[8:9], 0, s[98:99]
	s_waitcnt vmcnt(2)
	s_barrier
	global_load_lds_dwordx4 v[8:9], off
	v_lshl_add_u64 v[4:5], v[4:5], 0, s[98:99]
	s_add_i32 m0, s37, 0x1a000
	s_add_i32 s44, s37, 0x8000
	global_load_lds_dwordx4 v[4:5], off
	v_lshl_add_u64 v[4:5], v[6:7], 0, s[98:99]
	s_mov_b32 m0, s44
	s_add_i32 s45, s37, 0xa000
	global_load_lds_dwordx4 v[4:5], off
	v_lshl_add_u64 v[4:5], v[10:11], 0, s[98:99]
	s_mov_b32 m0, s45
	v_lshl_add_u64 v[2:3], v[2:3], 0, s[98:99]
	global_load_lds_dwordx4 v[4:5], off
	s_add_i32 m0, s37, 0x1c000
	v_lshl_add_u64 v[0:1], v[0:1], 0, s[98:99]
	global_load_lds_dwordx4 v[2:3], off
	s_add_i32 m0, s37, 0x1e000
	s_lshl_b32 s1, s1, 5
	global_load_lds_dwordx4 v[0:1], off
	v_lshrrev_b32_e32 v1, 1, v12
	v_and_b32_e32 v1, 24, v1
	v_and_b32_e32 v0, 15, v12
	v_lshlrev_b32_e32 v2, 1, v1
	v_lshl_or_b32 v135, s14, 6, v0
	v_lshl_or_b32 v0, v0, 6, v2
	v_lshlrev_b32_e32 v2, 2, v12
	s_lshr_b32 s15, s25, 26
	s_lshl_b32 s14, s14, 13
	v_and_b32_e32 v2, 32, v2
	s_and_b32 s1, s1, 0x60
	s_add_i32 s15, s24, s15
	v_bitop3_b32 v3, v0, s14, v2 bitop3:0xde
	s_lshl_b32 s14, s1, 7
	s_ashr_i32 s46, s15, 6
	v_bitop3_b32 v137, v0, s14, v2 bitop3:0xde
	v_add_u32_e32 v0, v18, v16
	s_cmp_gt_i32 s24, 63
	v_or_b32_e32 v154, s1, v1
	v_add_lshl_u32 v0, v0, v17, 1
	v_mov_b32_e32 v1, v129
	s_waitcnt vmcnt(6)
	s_cselect_b64 s[14:15], -1, 0
	s_add_i32 s47, s46, -2
	v_lshl_add_u64 v[146:147], s[2:3], 0, v[0:1]
	v_add_u32_e32 v0, v15, v13
	s_cmpk_lt_u32 s0, 0x100
	v_add_lshl_u32 v0, v0, v14, 1
	s_cselect_b64 s[16:17], -1, 0
	s_waitcnt lgkmcnt(0)
	s_ashr_i32 s48, s43, 31
	v_lshl_add_u64 v[148:149], s[2:3], 0, v[0:1]
	s_mov_b32 s49, 0
	v_add_u32_e32 v155, 16, v3
	v_readlane_b32 s52, v254, 51
	v_readlane_b32 s53, v254, 56
	s_barrier
	s_mov_b32 s101, 0
	s_branch .LBB0_327

.LBB0_339:
	s_cmp_eq_u32 s26, 0
	s_cselect_b32 s100, s101, 0
	s_add_i32 s54, s26, 2
	s_add_u32 s55, s0, 0x80
	s_addc_u32 s27, s1, 0
	s_add_i32 s58, 16, 0x10000
	s_cmp_eq_u32 s47, s26
	s_cselect_b32 s27, s21, s27
	s_cselect_b32 s26, s20, s55
	s_cselect_b32 s57, s25, s29
	s_cselect_b32 s56, s24, s28
	s_add_i32 s55, 16, 0x14000
	v_add_u32_e32 v164, s58, v137
	v_add_u32_e32 v180, s55, v137
	ds_read_b128 v[150:153], v164
	ds_read_b128 v[156:159], v164 offset:1024
	ds_read_b128 v[160:163], v164 offset:2048
	ds_read_b128 v[164:167], v164 offset:3072
	ds_read_b128 v[168:171], v180
	ds_read_b128 v[172:175], v180 offset:1024
	ds_read_b128 v[176:179], v180 offset:2048
	ds_read_b128 v[180:183], v180 offset:3072
	v_lshl_add_u64 v[236:237], s[0:1], 0, v[146:147]
	s_add_i32 m0, s37, 0xc000
	ds_read_b128 v[184:187], v155
	ds_read_b128 v[188:191], v155 offset:1024
	ds_read_b128 v[192:195], v155 offset:2048
	ds_read_b128 v[196:199], v155 offset:3072
	ds_read_b128 v[220:223], v155 offset:4096
	ds_read_b128 v[224:227], v155 offset:5120
	ds_read_b128 v[228:231], v155 offset:6144
	ds_read_b128 v[232:235], v155 offset:7168
	global_load_lds_dwordx4 v[236:237], off
	v_lshl_add_u64 v[236:237], s[0:1], 0, v[148:149]
	s_add_i32 m0, s37, 0xe000
	s_nop 0
	global_load_lds_dwordx4 v[236:237], off
	s_cmp_eq_u32 s100, 0
	s_cbranch_scc1 .Lgw8_3_0
	s_cmp_eq_u32 s100, 8
	s_cbranch_scc1 .Lgw16_3_0
	s_waitcnt vmcnt(24)
	s_branch .Lgwd_3_0

.Lgwd_3_0:
	s_waitcnt lgkmcnt(0)
	s_barrier
	s_setprio 1
	s_waitcnt lgkmcnt(0)
	v_mfma_f32_16x16x32_bf16 v[120:123], v[150:153], v[184:187], v[120:123]
	v_mfma_f32_16x16x32_bf16 v[124:127], v[160:163], v[184:187], v[124:127]
	v_mfma_f32_16x16x32_bf16 v[108:111], v[150:153], v[192:195], v[108:111]
	v_mfma_f32_16x16x32_bf16 v[104:107], v[160:163], v[192:195], v[104:107]
	v_mfma_f32_16x16x32_bf16 v[92:95], v[150:153], v[220:223], v[92:95]
	v_mfma_f32_16x16x32_bf16 v[88:91], v[160:163], v[220:223], v[88:91]
	v_mfma_f32_16x16x32_bf16 v[76:79], v[150:153], v[228:231], v[76:79]
	v_mfma_f32_16x16x32_bf16 v[72:75], v[160:163], v[228:231], v[72:75]
	v_mfma_f32_16x16x32_bf16 v[120:123], v[156:159], v[188:191], v[120:123]
	v_mfma_f32_16x16x32_bf16 v[124:127], v[164:167], v[188:191], v[124:127]
	v_mfma_f32_16x16x32_bf16 v[108:111], v[156:159], v[196:199], v[108:111]
	v_mfma_f32_16x16x32_bf16 v[104:107], v[164:167], v[196:199], v[104:107]
	v_mfma_f32_16x16x32_bf16 v[92:95], v[156:159], v[224:227], v[92:95]
	v_mfma_f32_16x16x32_bf16 v[88:91], v[164:167], v[224:227], v[88:91]
	v_mfma_f32_16x16x32_bf16 v[76:79], v[156:159], v[232:235], v[76:79]
	v_mfma_f32_16x16x32_bf16 v[72:75], v[164:167], v[232:235], v[72:75]
	s_setprio 0
	s_setprio 1
	v_mfma_f32_16x16x32_bf16 v[116:119], v[168:171], v[184:187], v[116:119]
	v_mfma_f32_16x16x32_bf16 v[112:115], v[176:179], v[184:187], v[112:115]
	v_mfma_f32_16x16x32_bf16 v[100:103], v[168:171], v[192:195], v[100:103]
	v_mfma_f32_16x16x32_bf16 v[96:99], v[176:179], v[192:195], v[96:99]
	v_mfma_f32_16x16x32_bf16 v[84:87], v[168:171], v[220:223], v[84:87]
	v_mfma_f32_16x16x32_bf16 v[80:83], v[176:179], v[220:223], v[80:83]
	v_mfma_f32_16x16x32_bf16 v[68:71], v[168:171], v[228:231], v[68:71]
	v_mfma_f32_16x16x32_bf16 v[64:67], v[176:179], v[228:231], v[64:67]
	v_mfma_f32_16x16x32_bf16 v[116:119], v[172:175], v[188:191], v[116:119]
	v_mfma_f32_16x16x32_bf16 v[112:115], v[180:183], v[188:191], v[112:115]
	v_mfma_f32_16x16x32_bf16 v[100:103], v[172:175], v[196:199], v[100:103]
	v_mfma_f32_16x16x32_bf16 v[96:99], v[180:183], v[196:199], v[96:99]
	v_mfma_f32_16x16x32_bf16 v[84:87], v[172:175], v[224:227], v[84:87]
	v_mfma_f32_16x16x32_bf16 v[80:83], v[180:183], v[224:227], v[80:83]
	v_mfma_f32_16x16x32_bf16 v[68:71], v[172:175], v[232:235], v[68:71]
	v_mfma_f32_16x16x32_bf16 v[64:67], v[180:183], v[232:235], v[64:67]
	s_setprio 0
	s_barrier
	s_add_i32 s58, s58, s34
	v_lshl_add_u64 v[236:237], s[56:57], 0, v[128:129]
	s_mov_b32 m0, s58
	ds_read_b128 v[184:187], v155 offset:16384
	ds_read_b128 v[188:191], v155 offset:17408
	ds_read_b128 v[192:195], v155 offset:18432
	ds_read_b128 v[196:199], v155 offset:19456
	ds_read_b128 v[220:223], v155 offset:20480
	ds_read_b128 v[224:227], v155 offset:21504
	ds_read_b128 v[228:231], v155 offset:22528
	ds_read_b128 v[232:235], v155 offset:23552
	global_load_lds_dwordx4 v[236:237], off
	s_add_i32 m0, s58, 0x2000
	v_lshl_add_u64 v[238:239], s[56:57], 0, v[140:141]
	s_add_u32 s56, s56, s2
	s_addc_u32 s57, s57, s3
	s_add_i32 s55, s55, s34
	global_load_lds_dwordx4 v[238:239], off
	v_lshl_add_u64 v[244:245], s[56:57], 0, v[128:129]
	s_mov_b32 m0, s55
	v_lshl_add_u64 v[246:247], s[56:57], 0, v[140:141]
	global_load_lds_dwordx4 v[244:245], off
	s_add_i32 m0, s55, 0x2000
	v_lshl_add_u64 v[248:249], s[26:27], 0, v[144:145]
	global_load_lds_dwordx4 v[246:247], off
	s_mov_b32 m0, s37
	v_lshl_add_u64 v[250:251], s[26:27], 0, v[142:143]
	global_load_lds_dwordx4 v[248:249], off
	s_mov_b32 m0, s38
	s_nop 0
	global_load_lds_dwordx4 v[250:251], off
	s_cmp_eq_u32 s100, 0
	s_cbranch_scc1 .Lgw8_3_1
	s_cmp_eq_u32 s100, 8
	s_cbranch_scc1 .Lgw16_3_1
	s_waitcnt vmcnt(24)
	s_branch .Lgwd_3_1

.Lgwd_3_1:
	s_waitcnt lgkmcnt(0)
	s_barrier
	s_setprio 1
	s_waitcnt lgkmcnt(0)
	v_mfma_f32_16x16x32_bf16 v[60:63], v[150:153], v[184:187], v[60:63]
	v_mfma_f32_16x16x32_bf16 v[56:59], v[160:163], v[184:187], v[56:59]
	v_mfma_f32_16x16x32_bf16 v[44:47], v[150:153], v[192:195], v[44:47]
	v_mfma_f32_16x16x32_bf16 v[40:43], v[160:163], v[192:195], v[40:43]
	v_mfma_f32_16x16x32_bf16 v[28:31], v[150:153], v[220:223], v[28:31]
	v_mfma_f32_16x16x32_bf16 v[24:27], v[160:163], v[220:223], v[24:27]
	v_mfma_f32_16x16x32_bf16 v[12:15], v[150:153], v[228:231], v[12:15]
	v_mfma_f32_16x16x32_bf16 v[8:11], v[160:163], v[228:231], v[8:11]
	v_mfma_f32_16x16x32_bf16 v[60:63], v[156:159], v[188:191], v[60:63]
	v_mfma_f32_16x16x32_bf16 v[56:59], v[164:167], v[188:191], v[56:59]
	v_mfma_f32_16x16x32_bf16 v[44:47], v[156:159], v[196:199], v[44:47]
	v_mfma_f32_16x16x32_bf16 v[40:43], v[164:167], v[196:199], v[40:43]
	v_mfma_f32_16x16x32_bf16 v[28:31], v[156:159], v[224:227], v[28:31]
	v_mfma_f32_16x16x32_bf16 v[24:27], v[164:167], v[224:227], v[24:27]
	v_mfma_f32_16x16x32_bf16 v[12:15], v[156:159], v[232:235], v[12:15]
	v_mfma_f32_16x16x32_bf16 v[8:11], v[164:167], v[232:235], v[8:11]
	s_setprio 0
	s_setprio 1
	v_mfma_f32_16x16x32_bf16 v[52:55], v[168:171], v[184:187], v[52:55]
	v_mfma_f32_16x16x32_bf16 v[48:51], v[176:179], v[184:187], v[48:51]
	v_mfma_f32_16x16x32_bf16 v[36:39], v[168:171], v[192:195], v[36:39]
	v_mfma_f32_16x16x32_bf16 v[32:35], v[176:179], v[192:195], v[32:35]
	v_mfma_f32_16x16x32_bf16 v[20:23], v[168:171], v[220:223], v[20:23]
	v_mfma_f32_16x16x32_bf16 v[16:19], v[176:179], v[220:223], v[16:19]
	v_mfma_f32_16x16x32_bf16 v[4:7], v[168:171], v[228:231], v[4:7]
	v_mfma_f32_16x16x32_bf16 v[0:3], v[176:179], v[228:231], v[0:3]
	v_mfma_f32_16x16x32_bf16 v[52:55], v[172:175], v[188:191], v[52:55]
	v_mfma_f32_16x16x32_bf16 v[48:51], v[180:183], v[188:191], v[48:51]
	v_mfma_f32_16x16x32_bf16 v[36:39], v[172:175], v[196:199], v[36:39]
	v_mfma_f32_16x16x32_bf16 v[32:35], v[180:183], v[196:199], v[32:35]
	v_mfma_f32_16x16x32_bf16 v[20:23], v[172:175], v[224:227], v[20:23]
	v_mfma_f32_16x16x32_bf16 v[16:19], v[180:183], v[224:227], v[16:19]
	v_mfma_f32_16x16x32_bf16 v[4:7], v[172:175], v[232:235], v[4:7]
	v_mfma_f32_16x16x32_bf16 v[0:3], v[180:183], v[232:235], v[0:3]
	s_setprio 0
	s_barrier
	s_add_i32 s55, 16, 0x18000
	s_add_i32 s56, 16, 0x1c000
	v_add_u32_e32 v164, s55, v137
	v_add_u32_e32 v180, s56, v137
	ds_read_b128 v[150:153], v164
	ds_read_b128 v[156:159], v164 offset:1024
	ds_read_b128 v[160:163], v164 offset:2048
	ds_read_b128 v[164:167], v164 offset:3072
	ds_read_b128 v[168:171], v180
	ds_read_b128 v[172:175], v180 offset:1024
	ds_read_b128 v[176:179], v180 offset:2048
	ds_read_b128 v[180:183], v180 offset:3072
	s_add_u32 s26, s26, s2
	s_addc_u32 s27, s27, s3
	s_mov_b32 m0, s39
	v_lshl_add_u64 v[208:209], s[26:27], 0, v[144:145]
	ds_read_b128 v[184:187], v155 offset:32768
	ds_read_b128 v[188:191], v155 offset:33792
	ds_read_b128 v[192:195], v155 offset:34816
	ds_read_b128 v[196:199], v155 offset:35840
	ds_read_b128 v[220:223], v155 offset:36864
	ds_read_b128 v[224:227], v155 offset:37888
	ds_read_b128 v[228:231], v155 offset:38912
	ds_read_b128 v[232:235], v155 offset:39936
	global_load_lds_dwordx4 v[208:209], off
	v_lshl_add_u64 v[208:209], s[26:27], 0, v[142:143]
	s_mov_b32 m0, s42
	s_nop 0
	global_load_lds_dwordx4 v[208:209], off
	s_waitcnt vmcnt(8)
	s_waitcnt lgkmcnt(0)
	s_barrier
	s_setprio 1
	s_waitcnt lgkmcnt(0)
	v_mfma_f32_16x16x32_bf16 v[120:123], v[150:153], v[184:187], v[120:123]
	v_mfma_f32_16x16x32_bf16 v[124:127], v[160:163], v[184:187], v[124:127]
	v_mfma_f32_16x16x32_bf16 v[108:111], v[150:153], v[192:195], v[108:111]
	v_mfma_f32_16x16x32_bf16 v[104:107], v[160:163], v[192:195], v[104:107]
	v_mfma_f32_16x16x32_bf16 v[92:95], v[150:153], v[220:223], v[92:95]
	v_mfma_f32_16x16x32_bf16 v[88:91], v[160:163], v[220:223], v[88:91]
	v_mfma_f32_16x16x32_bf16 v[76:79], v[150:153], v[228:231], v[76:79]
	v_mfma_f32_16x16x32_bf16 v[72:75], v[160:163], v[228:231], v[72:75]
	v_mfma_f32_16x16x32_bf16 v[120:123], v[156:159], v[188:191], v[120:123]
	v_mfma_f32_16x16x32_bf16 v[124:127], v[164:167], v[188:191], v[124:127]
	v_mfma_f32_16x16x32_bf16 v[108:111], v[156:159], v[196:199], v[108:111]
	v_mfma_f32_16x16x32_bf16 v[104:107], v[164:167], v[196:199], v[104:107]
	v_mfma_f32_16x16x32_bf16 v[92:95], v[156:159], v[224:227], v[92:95]
	v_mfma_f32_16x16x32_bf16 v[88:91], v[164:167], v[224:227], v[88:91]
	v_mfma_f32_16x16x32_bf16 v[76:79], v[156:159], v[232:235], v[76:79]
	v_mfma_f32_16x16x32_bf16 v[72:75], v[164:167], v[232:235], v[72:75]
	s_setprio 0
	s_setprio 1
	v_mfma_f32_16x16x32_bf16 v[116:119], v[168:171], v[184:187], v[116:119]
	v_mfma_f32_16x16x32_bf16 v[112:115], v[176:179], v[184:187], v[112:115]
	v_mfma_f32_16x16x32_bf16 v[100:103], v[168:171], v[192:195], v[100:103]
	v_mfma_f32_16x16x32_bf16 v[96:99], v[176:179], v[192:195], v[96:99]
	v_mfma_f32_16x16x32_bf16 v[84:87], v[168:171], v[220:223], v[84:87]
	v_mfma_f32_16x16x32_bf16 v[80:83], v[176:179], v[220:223], v[80:83]
	v_mfma_f32_16x16x32_bf16 v[68:71], v[168:171], v[228:231], v[68:71]
	v_mfma_f32_16x16x32_bf16 v[64:67], v[176:179], v[228:231], v[64:67]
	v_mfma_f32_16x16x32_bf16 v[116:119], v[172:175], v[188:191], v[116:119]
	v_mfma_f32_16x16x32_bf16 v[112:115], v[180:183], v[188:191], v[112:115]
	v_mfma_f32_16x16x32_bf16 v[100:103], v[172:175], v[196:199], v[100:103]
	v_mfma_f32_16x16x32_bf16 v[96:99], v[180:183], v[196:199], v[96:99]
	v_mfma_f32_16x16x32_bf16 v[84:87], v[172:175], v[224:227], v[84:87]
	v_mfma_f32_16x16x32_bf16 v[80:83], v[180:183], v[224:227], v[80:83]
	v_mfma_f32_16x16x32_bf16 v[68:71], v[172:175], v[232:235], v[68:71]
	v_mfma_f32_16x16x32_bf16 v[64:67], v[180:183], v[232:235], v[64:67]
	s_setprio 0
	s_barrier
	s_add_i32 s26, s55, s34
	v_lshl_add_u64 v[208:209], v[236:237], 0, s[98:99]
	s_mov_b32 m0, s26
	ds_read_b128 v[184:187], v155 offset:49152
	ds_read_b128 v[188:191], v155 offset:50176
	ds_read_b128 v[192:195], v155 offset:51200
	ds_read_b128 v[196:199], v155 offset:52224
	ds_read_b128 v[220:223], v155 offset:53248
	ds_read_b128 v[224:227], v155 offset:54272
	ds_read_b128 v[228:231], v155 offset:55296
	ds_read_b128 v[232:235], v155 offset:56320
	global_load_lds_dwordx4 v[208:209], off
	v_lshl_add_u64 v[208:209], v[238:239], 0, s[98:99]
	s_add_i32 m0, s26, 0x2000
	s_add_i32 s26, s56, s34
	global_load_lds_dwordx4 v[208:209], off
	v_lshl_add_u64 v[208:209], v[244:245], 0, s[98:99]
	s_mov_b32 m0, s26
	s_nop 0
	global_load_lds_dwordx4 v[208:209], off
	v_lshl_add_u64 v[208:209], v[246:247], 0, s[98:99]
	s_add_i32 m0, s26, 0x2000
	s_nop 0
	global_load_lds_dwordx4 v[208:209], off
	v_lshl_add_u64 v[208:209], v[248:249], 0, s[98:99]
	s_mov_b32 m0, s44
	s_nop 0
	global_load_lds_dwordx4 v[208:209], off
	v_lshl_add_u64 v[208:209], v[250:251], 0, s[98:99]
	s_mov_b32 m0, s45
	s_nop 0
	global_load_lds_dwordx4 v[208:209], off
	s_waitcnt vmcnt(8)
	s_waitcnt lgkmcnt(0)
	s_barrier
	s_setprio 1
	s_waitcnt lgkmcnt(0)
	v_mfma_f32_16x16x32_bf16 v[60:63], v[150:153], v[184:187], v[60:63]
	v_mfma_f32_16x16x32_bf16 v[56:59], v[160:163], v[184:187], v[56:59]
	v_mfma_f32_16x16x32_bf16 v[44:47], v[150:153], v[192:195], v[44:47]
	v_mfma_f32_16x16x32_bf16 v[40:43], v[160:163], v[192:195], v[40:43]
	v_mfma_f32_16x16x32_bf16 v[28:31], v[150:153], v[220:223], v[28:31]
	v_mfma_f32_16x16x32_bf16 v[24:27], v[160:163], v[220:223], v[24:27]
	v_mfma_f32_16x16x32_bf16 v[12:15], v[150:153], v[228:231], v[12:15]
	v_mfma_f32_16x16x32_bf16 v[8:11], v[160:163], v[228:231], v[8:11]
	v_mfma_f32_16x16x32_bf16 v[60:63], v[156:159], v[188:191], v[60:63]
	v_mfma_f32_16x16x32_bf16 v[56:59], v[164:167], v[188:191], v[56:59]
	v_mfma_f32_16x16x32_bf16 v[44:47], v[156:159], v[196:199], v[44:47]
	v_mfma_f32_16x16x32_bf16 v[40:43], v[164:167], v[196:199], v[40:43]
	v_mfma_f32_16x16x32_bf16 v[28:31], v[156:159], v[224:227], v[28:31]
	v_mfma_f32_16x16x32_bf16 v[24:27], v[164:167], v[224:227], v[24:27]
	v_mfma_f32_16x16x32_bf16 v[12:15], v[156:159], v[232:235], v[12:15]
	v_mfma_f32_16x16x32_bf16 v[8:11], v[164:167], v[232:235], v[8:11]
	s_setprio 0
	s_setprio 1
	v_mfma_f32_16x16x32_bf16 v[52:55], v[168:171], v[184:187], v[52:55]
	v_mfma_f32_16x16x32_bf16 v[48:51], v[176:179], v[184:187], v[48:51]
	v_mfma_f32_16x16x32_bf16 v[36:39], v[168:171], v[192:195], v[36:39]
	v_mfma_f32_16x16x32_bf16 v[32:35], v[176:179], v[192:195], v[32:35]
	v_mfma_f32_16x16x32_bf16 v[20:23], v[168:171], v[220:223], v[20:23]
	v_mfma_f32_16x16x32_bf16 v[16:19], v[176:179], v[220:223], v[16:19]
	v_mfma_f32_16x16x32_bf16 v[4:7], v[168:171], v[228:231], v[4:7]
	v_mfma_f32_16x16x32_bf16 v[0:3], v[176:179], v[228:231], v[0:3]
	v_mfma_f32_16x16x32_bf16 v[52:55], v[172:175], v[188:191], v[52:55]
	v_mfma_f32_16x16x32_bf16 v[48:51], v[180:183], v[188:191], v[48:51]
	v_mfma_f32_16x16x32_bf16 v[36:39], v[172:175], v[196:199], v[36:39]
	v_mfma_f32_16x16x32_bf16 v[32:35], v[180:183], v[196:199], v[32:35]
	v_mfma_f32_16x16x32_bf16 v[20:23], v[172:175], v[224:227], v[20:23]
	v_mfma_f32_16x16x32_bf16 v[16:19], v[180:183], v[224:227], v[16:19]
	v_mfma_f32_16x16x32_bf16 v[4:7], v[172:175], v[232:235], v[4:7]
	v_mfma_f32_16x16x32_bf16 v[0:3], v[180:183], v[232:235], v[0:3]
	s_setprio 0
	s_barrier
	s_add_u32 s0, s0, 0x100
	s_addc_u32 s1, s1, 0
	s_add_u32 s28, s28, 0x100
	s_addc_u32 s29, s29, 0
	s_cmp_ge_i32 s54, s46
	s_mov_b32 s26, s54
	s_cbranch_scc0 .LBB0_339
	v_readlane_b32 s58, v255, 20
	v_readlane_b32 s59, v255, 21

.LBB0_343:
	s_cmp_eq_u32 s52, 15
	s_cselect_b32 s101, 8, 16
	v_lshl_add_u32 v156, s53, 8, v135
	v_lshl_or_b32 v150, s52, 8, v154
	v_mov_b64_e32 v[152:153], s[22:23]
	v_ashrrev_i32_e32 v151, 31, v150
	v_mad_i64_i32 v[152:153], s[0:1], v156, s93, v[152:153]
	v_lshl_add_u64 v[152:153], v[150:151], 1, v[152:153]
	v_cmp_gt_i32_e32 vcc, s94, v150
	s_and_saveexec_b64 s[0:1], vcc
	s_cbranch_execz .LBB0_345
	v_cvt_pk_bf16_f32 v120, v120, v121
	v_cvt_pk_bf16_f32 v121, v122, v123
	v_cvt_pk_bf16_f32 v122, v124, v125
	v_cvt_pk_bf16_f32 v123, v126, v127
	global_store_dwordx4 v[152:153], v[120:123], off

	.amdhsa_kernel _Z10hybrid_fwd6Params
		.amdhsa_group_segment_fixed_size 16
		.amdhsa_private_segment_fixed_size 0
		.amdhsa_kernarg_size 392
		.amdhsa_user_sgpr_count 2
		.amdhsa_user_sgpr_dispatch_ptr 0
		.amdhsa_user_sgpr_queue_ptr 0
		.amdhsa_user_sgpr_kernarg_segment_ptr 1
		.amdhsa_user_sgpr_dispatch_id 0
		.amdhsa_user_sgpr_kernarg_preload_length 0
		.amdhsa_user_sgpr_kernarg_preload_offset 0
		.amdhsa_user_sgpr_private_segment_size 0
		.amdhsa_uses_dynamic_stack 0
		.amdhsa_enable_private_segment 0
		.amdhsa_system_sgpr_workgroup_id_x 1
		.amdhsa_system_sgpr_workgroup_id_y 0
		.amdhsa_system_sgpr_workgroup_id_z 0
		.amdhsa_system_sgpr_workgroup_info 0
		.amdhsa_system_vgpr_workitem_id 2
		.amdhsa_next_free_vgpr 256
		.amdhsa_next_free_sgpr 102
		.amdhsa_accum_offset 256
		.amdhsa_reserve_vcc 1
		.amdhsa_float_round_mode_32 0
		.amdhsa_float_round_mode_16_64 0
		.amdhsa_float_denorm_mode_32 3
		.amdhsa_float_denorm_mode_16_64 3
		.amdhsa_dx10_clamp 1
		.amdhsa_ieee_mode 1
		.amdhsa_fp16_overflow 0
		.amdhsa_tg_split 0
		.amdhsa_exception_fp_ieee_invalid_op 0
		.amdhsa_exception_fp_denorm_src 0
		.amdhsa_exception_fp_ieee_div_zero 0
		.amdhsa_exception_fp_ieee_overflow 0
		.amdhsa_exception_fp_ieee_underflow 0
		.amdhsa_exception_fp_ieee_inexact 0
		.amdhsa_exception_int_div_zero 0
	.end_amdhsa_kernel

amdhsa.kernels:
  - .agpr_count:     0
    .args:
      - .offset:         0
        .size:           136
        .value_kind:     by_value
      - .offset:         136
        .size:           4
        .value_kind:     hidden_block_count_x
      - .offset:         140
        .size:           4
        .value_kind:     hidden_block_count_y
      - .offset:         144
        .size:           4
        .value_kind:     hidden_block_count_z
      - .offset:         148
        .size:           2
        .value_kind:     hidden_group_size_x
      - .offset:         150
        .size:           2
        .value_kind:     hidden_group_size_y
      - .offset:         152
        .size:           2
        .value_kind:     hidden_group_size_z
      - .offset:         154
        .size:           2
        .value_kind:     hidden_remainder_x
      - .offset:         156
        .size:           2
        .value_kind:     hidden_remainder_y
      - .offset:         158
        .size:           2
        .value_kind:     hidden_remainder_z
      - .offset:         176
        .size:           8
        .value_kind:     hidden_global_offset_x
      - .offset:         184
        .size:           8
        .value_kind:     hidden_global_offset_y
      - .offset:         192
        .size:           8
        .value_kind:     hidden_global_offset_z
      - .offset:         200
        .size:           2
        .value_kind:     hidden_grid_dims
      - .offset:         224
        .size:           8
        .value_kind:     hidden_multigrid_sync_arg
      - .offset:         256
        .size:           4
        .value_kind:     hidden_dynamic_lds_size
    .group_segment_fixed_size: 16
    .kernarg_segment_align: 8
    .kernarg_segment_size: 392
    .language:       OpenCL C
    .language_version:
      - 2
      - 0
    .max_flat_workgroup_size: 512
    .name:           _Z10hybrid_fwd6Params
    .private_segment_fixed_size: 0
    .sgpr_count:     108
    .sgpr_spill_count: 178
    .symbol:         _Z10hybrid_fwd6Params.kd
    .uniform_work_group_size: 1
    .uses_dynamic_stack: false
    .vgpr_count:     256
    .vgpr_spill_count: 0
    .wavefront_size: 64
